# PEER gather rewritten by hand as 4 column-sliced sub-phases (A dots, B gelu/gate, C axpy+residual, D LayerNorm), each XCD keeps a 2MB table slice in L2; f32 FMA on fp8->f32 converted rows as baseline
# speedup vs baseline: 1.7250x; 1.7250x over previous
.LBB1_30:
	s_add_i32 s2, s26, 1
	s_cmp_gt_u32 s26, 14
	s_mov_b32 s26, s2
	v_readlane_b32 s8, v241, 24
	v_readlane_b32 s10, v241, 26
	v_readlane_b32 s12, v240, 18
	v_readlane_b32 s9, v241, 25
	v_readlane_b32 s11, v241, 27
	v_readlane_b32 s13, v240, 19
	s_cbranch_scc1 .LBB1_26
.LBB1_31:
	s_movk_i32 s58, 0x41ff
	s_mov_b64 s[30:31], -1
	s_mov_b64 s[38:39], 0
	s_cmp_lt_i32 s26, 7
	s_mov_b64 s[28:29], 0
	s_cbranch_scc1 .LBB1_93
	s_cmp_gt_i32 s26, 8
	s_cbranch_scc0 .LBB1_76
	s_cmp_gt_i32 s26, 9
	s_cbranch_scc0 .LBB1_70
	s_cmp_gt_i32 s26, 11
	s_mov_b64 s[40:41], -1
	s_cbranch_scc0 .LBB1_49
	s_mov_b64 exec, -1
	s_cmp_eq_u32 s26, 12
	s_cbranch_scc1 .Lgy_A_1
	s_cmp_eq_u32 s26, 13
	s_cbranch_scc1 .Lgy_B_2
	s_cmp_eq_u32 s26, 14
	s_cbranch_scc1 .Lgy_C_3
	s_branch .Lgy_D_4
.Lgy_A_1:
	v_lshrrev_b32_e32 v142, 6, v162
	v_readlane_b32 s2, v242, 0
	v_readlane_b32 s59, v241, 24
	v_readfirstlane_b32 s29, v142
	s_and_b32 s28, s2, 7
	s_lshr_b32 s2, s2, 3
	s_lshl_b32 s2, s2, 2
	s_add_u32 s54, s2, s29
	s_lshr_b32 s59, s59, 3
	s_load_dwordx2 s[88:89], s[0:1], 0x1a8
	s_load_dwordx2 s[92:93], s[0:1], 0x130
	v_readlane_b32 s40, v240, 8
	v_readlane_b32 s41, v240, 9
	v_and_b32_e32 v142, 7, v168
	v_lshlrev_b32_e32 v160, 2, v168
	s_lshl_b32 s32, s28, 7
	v_lshl_add_u32 v138, v142, 4, s32
	v_and_b32_e32 v143, 0xf8, v168
	v_add_u32_e32 v130, 0, v143
	v_add_u32_e32 v131, 1, v143
	v_add_u32_e32 v132, 2, v143
	v_add_u32_e32 v133, 3, v143
	v_add_u32_e32 v134, 4, v143
	v_add_u32_e32 v135, 5, v143
	v_add_u32_e32 v136, 6, v143
	v_add_u32_e32 v137, 7, v143
	v_lshlrev_b32_e32 v130, 2, v130
	v_lshlrev_b32_e32 v131, 2, v131
	v_lshlrev_b32_e32 v132, 2, v132
	v_lshlrev_b32_e32 v133, 2, v133
	v_lshlrev_b32_e32 v134, 2, v134
	v_lshlrev_b32_e32 v135, 2, v135
	v_lshlrev_b32_e32 v136, 2, v136
	v_lshlrev_b32_e32 v137, 2, v137
	s_lshl_b32 s32, s28, 8
	v_lshl_add_u32 v161, v142, 5, s32
	s_mov_b32 s4, 0x01010101
	s_mov_b32 s5, 0x01010101
	s_mov_b32 s6, 0x02020202
	s_mov_b32 s7, 0x02020202
	s_mov_b32 s8, 0x04040404
	s_mov_b32 s9, 0x04040404
	s_mov_b32 s10, 0x08080808
	s_mov_b32 s11, 0x08080808
	s_mov_b32 s12, 0x10101010
	s_mov_b32 s13, 0x10101010
	s_mov_b32 s14, 0x20202020
	s_mov_b32 s15, 0x20202020
	s_mov_b32 s16, 0x40404040
	s_mov_b32 s17, 0x40404040
	s_mov_b32 s18, 0x80808080
	s_mov_b32 s19, 0x80808080
	s_waitcnt lgkmcnt(0)
	s_mul_i32 s32, s28, 0x840000
	s_add_u32 s92, s92, s32
	s_addc_u32 s93, s93, 0
	s_nop 4
	s_cmp_lt_u32 s54, 0x4200
	s_cbranch_scc0 .Lgy_Adone_6
	s_min_u32 s98, s54, 0x41ff
	s_lshl_b32 s98, s98, 9
	s_add_u32 s52, s88, s98
	s_addc_u32 s53, s89, 0
	global_load_dword v144, v160, s[52:53]
	global_load_dword v145, v160, s[52:53] offset:256
	s_add_u32 s99, s54, s59
	s_min_u32 s98, s99, 0x41ff
	s_lshl_b32 s98, s98, 9
	s_add_u32 s52, s88, s98
	s_addc_u32 s53, s89, 0
	global_load_dword v150, v160, s[52:53]
	global_load_dword v151, v160, s[52:53] offset:256
	s_min_u32 s98, s54, 0x41ff
	s_lshl_b32 s98, s98, 11
	s_add_u32 s52, s74, s98
	s_addc_u32 s53, s75, 0
	global_load_dwordx4 v[152:155], v161, s[52:53]
	global_load_dwordx4 v[156:159], v161, s[52:53] offset:16
	s_waitcnt vmcnt(0)
	ds_bpermute_b32 v16, v130, v144
	ds_bpermute_b32 v17, v131, v144
	ds_bpermute_b32 v18, v132, v144
	ds_bpermute_b32 v19, v133, v144
	ds_bpermute_b32 v20, v134, v144
	ds_bpermute_b32 v21, v135, v144
	ds_bpermute_b32 v22, v136, v144
	ds_bpermute_b32 v23, v137, v144
	ds_bpermute_b32 v24, v130, v145
	ds_bpermute_b32 v25, v131, v145
	ds_bpermute_b32 v26, v132, v145
	ds_bpermute_b32 v27, v133, v145
	ds_bpermute_b32 v28, v134, v145
	ds_bpermute_b32 v29, v135, v145
	ds_bpermute_b32 v30, v136, v145
	ds_bpermute_b32 v31, v137, v145
	s_waitcnt lgkmcnt(0)
	v_lshl_add_u32 v16, v16, 10, v138
	v_lshl_add_u32 v17, v17, 10, v138
	v_lshl_add_u32 v18, v18, 10, v138
	v_lshl_add_u32 v19, v19, 10, v138
	v_lshl_add_u32 v20, v20, 10, v138
	v_lshl_add_u32 v21, v21, 10, v138
	v_lshl_add_u32 v22, v22, 10, v138
	v_lshl_add_u32 v23, v23, 10, v138
	v_lshl_add_u32 v24, v24, 10, v138
	v_lshl_add_u32 v25, v25, 10, v138
	v_lshl_add_u32 v26, v26, 10, v138
	v_lshl_add_u32 v27, v27, 10, v138
	v_lshl_add_u32 v28, v28, 10, v138
	v_lshl_add_u32 v29, v29, 10, v138
	v_lshl_add_u32 v30, v30, 10, v138
	v_lshl_add_u32 v31, v31, 10, v138
	global_load_dwordx4 v[48:51], v16, s[40:41]
	global_load_dwordx4 v[52:55], v17, s[40:41]
	global_load_dwordx4 v[56:59], v18, s[40:41]
	global_load_dwordx4 v[60:63], v19, s[40:41]
	global_load_dwordx4 v[64:67], v20, s[40:41]
	global_load_dwordx4 v[68:71], v21, s[40:41]
	global_load_dwordx4 v[72:75], v22, s[40:41]
	global_load_dwordx4 v[76:79], v23, s[40:41]
	global_load_dwordx4 v[80:83], v24, s[40:41]
	global_load_dwordx4 v[84:87], v25, s[40:41]
	global_load_dwordx4 v[88:91], v26, s[40:41]
	global_load_dwordx4 v[92:95], v27, s[40:41]
	global_load_dwordx4 v[96:99], v28, s[40:41]
	global_load_dwordx4 v[100:103], v29, s[40:41]
	global_load_dwordx4 v[104:107], v30, s[40:41]
	global_load_dwordx4 v[108:111], v31, s[40:41]
	global_load_dword v146, v160, s[52:53]
	global_load_dword v147, v160, s[52:53]
	ds_bpermute_b32 v16, v130, v150
	ds_bpermute_b32 v17, v131, v150
	ds_bpermute_b32 v18, v132, v150
	ds_bpermute_b32 v19, v133, v150
	ds_bpermute_b32 v20, v134, v150
	ds_bpermute_b32 v21, v135, v150
	ds_bpermute_b32 v22, v136, v150
	ds_bpermute_b32 v23, v137, v150
	ds_bpermute_b32 v24, v130, v151
	ds_bpermute_b32 v25, v131, v151
	ds_bpermute_b32 v26, v132, v151
	ds_bpermute_b32 v27, v133, v151
	ds_bpermute_b32 v28, v134, v151
	ds_bpermute_b32 v29, v135, v151
	ds_bpermute_b32 v30, v136, v151
	ds_bpermute_b32 v31, v137, v151
	s_waitcnt lgkmcnt(0)
	v_lshl_add_u32 v16, v16, 10, v138
	v_lshl_add_u32 v17, v17, 10, v138
	v_lshl_add_u32 v18, v18, 10, v138
	v_lshl_add_u32 v19, v19, 10, v138
	v_lshl_add_u32 v20, v20, 10, v138
	v_lshl_add_u32 v21, v21, 10, v138
	v_lshl_add_u32 v22, v22, 10, v138
	v_lshl_add_u32 v23, v23, 10, v138
	v_lshl_add_u32 v24, v24, 10, v138
	v_lshl_add_u32 v25, v25, 10, v138
	v_lshl_add_u32 v26, v26, 10, v138
	v_lshl_add_u32 v27, v27, 10, v138
	v_lshl_add_u32 v28, v28, 10, v138
	v_lshl_add_u32 v29, v29, 10, v138
	v_lshl_add_u32 v30, v30, 10, v138
	v_lshl_add_u32 v31, v31, 10, v138
	v_lshlrev_b32_e32 v0, 16, v152
	v_and_b32_e32 v1, 0xffff0000, v152
	v_lshlrev_b32_e32 v2, 16, v153
	v_and_b32_e32 v3, 0xffff0000, v153
	v_lshlrev_b32_e32 v4, 16, v154
	v_and_b32_e32 v5, 0xffff0000, v154
	v_lshlrev_b32_e32 v6, 16, v155
	v_and_b32_e32 v7, 0xffff0000, v155
	v_lshlrev_b32_e32 v8, 16, v156
	v_and_b32_e32 v9, 0xffff0000, v156
	v_lshlrev_b32_e32 v10, 16, v157
	v_and_b32_e32 v11, 0xffff0000, v157
	v_lshlrev_b32_e32 v12, 16, v158
	v_and_b32_e32 v13, 0xffff0000, v158
	v_lshlrev_b32_e32 v14, 16, v159
	v_and_b32_e32 v15, 0xffff0000, v159
.Lgy_Atok_7:
	s_add_u32 s99, s54, s59
	s_add_u32 s96, s99, s59
	s_min_u32 s98, s96, 0x41ff
	s_lshl_b32 s98, s98, 9
	s_add_u32 s52, s88, s98
	s_addc_u32 s53, s89, 0
	global_load_dword v150, v160, s[52:53]
	global_load_dword v151, v160, s[52:53] offset:256
	s_min_u32 s98, s99, 0x41ff
	s_lshl_b32 s98, s98, 11
	s_add_u32 s52, s74, s98
	s_addc_u32 s53, s75, 0
	global_load_dwordx4 v[152:155], v161, s[52:53]
	global_load_dwordx4 v[156:159], v161, s[52:53] offset:16
	s_waitcnt vmcnt(19)
	v_cvt_pk_f32_fp8_e32 v[112:113], v48
	v_cvt_pk_f32_fp8_sdwa v[114:115], v48 src0_sel:WORD_1
	v_cvt_pk_f32_fp8_e32 v[116:117], v49
	v_cvt_pk_f32_fp8_sdwa v[118:119], v49 src0_sel:WORD_1
	v_cvt_pk_f32_fp8_e32 v[120:121], v50
	v_cvt_pk_f32_fp8_sdwa v[122:123], v50 src0_sel:WORD_1
	v_cvt_pk_f32_fp8_e32 v[124:125], v51
	v_cvt_pk_f32_fp8_sdwa v[126:127], v51 src0_sel:WORD_1
	global_load_dwordx4 v[48:51], v16, s[40:41]
	v_pk_mul_f32 v[142:143], v[112:113], v[0:1]
	v_pk_mul_f32 v[144:145], v[114:115], v[2:3]
	v_pk_fma_f32 v[142:143], v[116:117], v[4:5], v[142:143]
	v_pk_fma_f32 v[144:145], v[118:119], v[6:7], v[144:145]
	v_pk_fma_f32 v[142:143], v[120:121], v[8:9], v[142:143]
	v_pk_fma_f32 v[144:145], v[122:123], v[10:11], v[144:145]
	v_pk_fma_f32 v[142:143], v[124:125], v[12:13], v[142:143]
	v_pk_fma_f32 v[144:145], v[126:127], v[14:15], v[144:145]
	s_nop 0
	v_pk_add_f32 v[142:143], v[142:143], v[144:145]
	s_nop 0
	v_add_f32_e32 v146, v142, v143
	s_nop 1
	v_add_f32_dpp v146, v146, v146 quad_perm:[1,0,3,2] row_mask:0xf bank_mask:0xf
	s_nop 1
	v_add_f32_dpp v146, v146, v146 quad_perm:[2,3,0,1] row_mask:0xf bank_mask:0xf
	s_nop 1
	v_add_f32_dpp v146, v146, v146 row_half_mirror row_mask:0xf bank_mask:0xf
	v_cndmask_b32_e64 v139, v139, v146, s[4:5]
	s_waitcnt vmcnt(19)
	v_cvt_pk_f32_fp8_e32 v[112:113], v52
	v_cvt_pk_f32_fp8_sdwa v[114:115], v52 src0_sel:WORD_1
	v_cvt_pk_f32_fp8_e32 v[116:117], v53
	v_cvt_pk_f32_fp8_sdwa v[118:119], v53 src0_sel:WORD_1
	v_cvt_pk_f32_fp8_e32 v[120:121], v54
	v_cvt_pk_f32_fp8_sdwa v[122:123], v54 src0_sel:WORD_1
	v_cvt_pk_f32_fp8_e32 v[124:125], v55
	v_cvt_pk_f32_fp8_sdwa v[126:127], v55 src0_sel:WORD_1
	global_load_dwordx4 v[52:55], v17, s[40:41]
	v_pk_mul_f32 v[142:143], v[112:113], v[0:1]
	v_pk_mul_f32 v[144:145], v[114:115], v[2:3]
	v_pk_fma_f32 v[142:143], v[116:117], v[4:5], v[142:143]
	v_pk_fma_f32 v[144:145], v[118:119], v[6:7], v[144:145]
	v_pk_fma_f32 v[142:143], v[120:121], v[8:9], v[142:143]
	v_pk_fma_f32 v[144:145], v[122:123], v[10:11], v[144:145]
	v_pk_fma_f32 v[142:143], v[124:125], v[12:13], v[142:143]
	v_pk_fma_f32 v[144:145], v[126:127], v[14:15], v[144:145]
	s_nop 0
	v_pk_add_f32 v[142:143], v[142:143], v[144:145]
	s_nop 0
	v_add_f32_e32 v146, v142, v143
	s_nop 1
	v_add_f32_dpp v146, v146, v146 quad_perm:[1,0,3,2] row_mask:0xf bank_mask:0xf
	s_nop 1
	v_add_f32_dpp v146, v146, v146 quad_perm:[2,3,0,1] row_mask:0xf bank_mask:0xf
	s_nop 1
	v_add_f32_dpp v146, v146, v146 row_half_mirror row_mask:0xf bank_mask:0xf
	v_cndmask_b32_e64 v139, v139, v146, s[6:7]
	s_waitcnt vmcnt(19)
	v_cvt_pk_f32_fp8_e32 v[112:113], v56
	v_cvt_pk_f32_fp8_sdwa v[114:115], v56 src0_sel:WORD_1
	v_cvt_pk_f32_fp8_e32 v[116:117], v57
	v_cvt_pk_f32_fp8_sdwa v[118:119], v57 src0_sel:WORD_1
	v_cvt_pk_f32_fp8_e32 v[120:121], v58
	v_cvt_pk_f32_fp8_sdwa v[122:123], v58 src0_sel:WORD_1
	v_cvt_pk_f32_fp8_e32 v[124:125], v59
	v_cvt_pk_f32_fp8_sdwa v[126:127], v59 src0_sel:WORD_1
	global_load_dwordx4 v[56:59], v18, s[40:41]
	v_pk_mul_f32 v[142:143], v[112:113], v[0:1]
	v_pk_mul_f32 v[144:145], v[114:115], v[2:3]
	v_pk_fma_f32 v[142:143], v[116:117], v[4:5], v[142:143]
	v_pk_fma_f32 v[144:145], v[118:119], v[6:7], v[144:145]
	v_pk_fma_f32 v[142:143], v[120:121], v[8:9], v[142:143]
	v_pk_fma_f32 v[144:145], v[122:123], v[10:11], v[144:145]
	v_pk_fma_f32 v[142:143], v[124:125], v[12:13], v[142:143]
	v_pk_fma_f32 v[144:145], v[126:127], v[14:15], v[144:145]
	s_nop 0
	v_pk_add_f32 v[142:143], v[142:143], v[144:145]
	s_nop 0
	v_add_f32_e32 v146, v142, v143
	s_nop 1
	v_add_f32_dpp v146, v146, v146 quad_perm:[1,0,3,2] row_mask:0xf bank_mask:0xf
	s_nop 1
	v_add_f32_dpp v146, v146, v146 quad_perm:[2,3,0,1] row_mask:0xf bank_mask:0xf
	s_nop 1
	v_add_f32_dpp v146, v146, v146 row_half_mirror row_mask:0xf bank_mask:0xf
	v_cndmask_b32_e64 v139, v139, v146, s[8:9]
	s_waitcnt vmcnt(19)
	v_cvt_pk_f32_fp8_e32 v[112:113], v60
	v_cvt_pk_f32_fp8_sdwa v[114:115], v60 src0_sel:WORD_1
	v_cvt_pk_f32_fp8_e32 v[116:117], v61
	v_cvt_pk_f32_fp8_sdwa v[118:119], v61 src0_sel:WORD_1
	v_cvt_pk_f32_fp8_e32 v[120:121], v62
	v_cvt_pk_f32_fp8_sdwa v[122:123], v62 src0_sel:WORD_1
	v_cvt_pk_f32_fp8_e32 v[124:125], v63
	v_cvt_pk_f32_fp8_sdwa v[126:127], v63 src0_sel:WORD_1
	global_load_dwordx4 v[60:63], v19, s[40:41]
	v_pk_mul_f32 v[142:143], v[112:113], v[0:1]
	v_pk_mul_f32 v[144:145], v[114:115], v[2:3]
	v_pk_fma_f32 v[142:143], v[116:117], v[4:5], v[142:143]
	v_pk_fma_f32 v[144:145], v[118:119], v[6:7], v[144:145]
	v_pk_fma_f32 v[142:143], v[120:121], v[8:9], v[142:143]
	v_pk_fma_f32 v[144:145], v[122:123], v[10:11], v[144:145]
	v_pk_fma_f32 v[142:143], v[124:125], v[12:13], v[142:143]
	v_pk_fma_f32 v[144:145], v[126:127], v[14:15], v[144:145]
	s_nop 0
	v_pk_add_f32 v[142:143], v[142:143], v[144:145]
	s_nop 0
	v_add_f32_e32 v146, v142, v143
	s_nop 1
	v_add_f32_dpp v146, v146, v146 quad_perm:[1,0,3,2] row_mask:0xf bank_mask:0xf
	s_nop 1
	v_add_f32_dpp v146, v146, v146 quad_perm:[2,3,0,1] row_mask:0xf bank_mask:0xf
	s_nop 1
	v_add_f32_dpp v146, v146, v146 row_half_mirror row_mask:0xf bank_mask:0xf
	v_cndmask_b32_e64 v139, v139, v146, s[10:11]
	s_waitcnt vmcnt(19)
	v_cvt_pk_f32_fp8_e32 v[112:113], v64
	v_cvt_pk_f32_fp8_sdwa v[114:115], v64 src0_sel:WORD_1
	v_cvt_pk_f32_fp8_e32 v[116:117], v65
	v_cvt_pk_f32_fp8_sdwa v[118:119], v65 src0_sel:WORD_1
	v_cvt_pk_f32_fp8_e32 v[120:121], v66
	v_cvt_pk_f32_fp8_sdwa v[122:123], v66 src0_sel:WORD_1
	v_cvt_pk_f32_fp8_e32 v[124:125], v67
	v_cvt_pk_f32_fp8_sdwa v[126:127], v67 src0_sel:WORD_1
	global_load_dwordx4 v[64:67], v20, s[40:41]
	v_pk_mul_f32 v[142:143], v[112:113], v[0:1]
	v_pk_mul_f32 v[144:145], v[114:115], v[2:3]
	v_pk_fma_f32 v[142:143], v[116:117], v[4:5], v[142:143]
	v_pk_fma_f32 v[144:145], v[118:119], v[6:7], v[144:145]
	v_pk_fma_f32 v[142:143], v[120:121], v[8:9], v[142:143]
	v_pk_fma_f32 v[144:145], v[122:123], v[10:11], v[144:145]
	v_pk_fma_f32 v[142:143], v[124:125], v[12:13], v[142:143]
	v_pk_fma_f32 v[144:145], v[126:127], v[14:15], v[144:145]
	s_nop 0
	v_pk_add_f32 v[142:143], v[142:143], v[144:145]
	s_nop 0
	v_add_f32_e32 v146, v142, v143
	s_nop 1
	v_add_f32_dpp v146, v146, v146 quad_perm:[1,0,3,2] row_mask:0xf bank_mask:0xf
	s_nop 1
	v_add_f32_dpp v146, v146, v146 quad_perm:[2,3,0,1] row_mask:0xf bank_mask:0xf
	s_nop 1
	v_add_f32_dpp v146, v146, v146 row_half_mirror row_mask:0xf bank_mask:0xf
	v_cndmask_b32_e64 v139, v139, v146, s[12:13]
	s_waitcnt vmcnt(19)
	v_cvt_pk_f32_fp8_e32 v[112:113], v68
	v_cvt_pk_f32_fp8_sdwa v[114:115], v68 src0_sel:WORD_1
	v_cvt_pk_f32_fp8_e32 v[116:117], v69
	v_cvt_pk_f32_fp8_sdwa v[118:119], v69 src0_sel:WORD_1
	v_cvt_pk_f32_fp8_e32 v[120:121], v70
	v_cvt_pk_f32_fp8_sdwa v[122:123], v70 src0_sel:WORD_1
	v_cvt_pk_f32_fp8_e32 v[124:125], v71
	v_cvt_pk_f32_fp8_sdwa v[126:127], v71 src0_sel:WORD_1
	global_load_dwordx4 v[68:71], v21, s[40:41]
	v_pk_mul_f32 v[142:143], v[112:113], v[0:1]
	v_pk_mul_f32 v[144:145], v[114:115], v[2:3]
	v_pk_fma_f32 v[142:143], v[116:117], v[4:5], v[142:143]
	v_pk_fma_f32 v[144:145], v[118:119], v[6:7], v[144:145]
	v_pk_fma_f32 v[142:143], v[120:121], v[8:9], v[142:143]
	v_pk_fma_f32 v[144:145], v[122:123], v[10:11], v[144:145]
	v_pk_fma_f32 v[142:143], v[124:125], v[12:13], v[142:143]
	v_pk_fma_f32 v[144:145], v[126:127], v[14:15], v[144:145]
	s_nop 0
	v_pk_add_f32 v[142:143], v[142:143], v[144:145]
	s_nop 0
	v_add_f32_e32 v146, v142, v143
	s_nop 1
	v_add_f32_dpp v146, v146, v146 quad_perm:[1,0,3,2] row_mask:0xf bank_mask:0xf
	s_nop 1
	v_add_f32_dpp v146, v146, v146 quad_perm:[2,3,0,1] row_mask:0xf bank_mask:0xf
	s_nop 1
	v_add_f32_dpp v146, v146, v146 row_half_mirror row_mask:0xf bank_mask:0xf
	v_cndmask_b32_e64 v139, v139, v146, s[14:15]
	s_waitcnt vmcnt(19)
	v_cvt_pk_f32_fp8_e32 v[112:113], v72
	v_cvt_pk_f32_fp8_sdwa v[114:115], v72 src0_sel:WORD_1
	v_cvt_pk_f32_fp8_e32 v[116:117], v73
	v_cvt_pk_f32_fp8_sdwa v[118:119], v73 src0_sel:WORD_1
	v_cvt_pk_f32_fp8_e32 v[120:121], v74
	v_cvt_pk_f32_fp8_sdwa v[122:123], v74 src0_sel:WORD_1
	v_cvt_pk_f32_fp8_e32 v[124:125], v75
	v_cvt_pk_f32_fp8_sdwa v[126:127], v75 src0_sel:WORD_1
	global_load_dwordx4 v[72:75], v22, s[40:41]
	v_pk_mul_f32 v[142:143], v[112:113], v[0:1]
	v_pk_mul_f32 v[144:145], v[114:115], v[2:3]
	v_pk_fma_f32 v[142:143], v[116:117], v[4:5], v[142:143]
	v_pk_fma_f32 v[144:145], v[118:119], v[6:7], v[144:145]
	v_pk_fma_f32 v[142:143], v[120:121], v[8:9], v[142:143]
	v_pk_fma_f32 v[144:145], v[122:123], v[10:11], v[144:145]
	v_pk_fma_f32 v[142:143], v[124:125], v[12:13], v[142:143]
	v_pk_fma_f32 v[144:145], v[126:127], v[14:15], v[144:145]
	s_nop 0
	v_pk_add_f32 v[142:143], v[142:143], v[144:145]
	s_nop 0
	v_add_f32_e32 v146, v142, v143
	s_nop 1
	v_add_f32_dpp v146, v146, v146 quad_perm:[1,0,3,2] row_mask:0xf bank_mask:0xf
	s_nop 1
	v_add_f32_dpp v146, v146, v146 quad_perm:[2,3,0,1] row_mask:0xf bank_mask:0xf
	s_nop 1
	v_add_f32_dpp v146, v146, v146 row_half_mirror row_mask:0xf bank_mask:0xf
	v_cndmask_b32_e64 v139, v139, v146, s[16:17]
	s_waitcnt vmcnt(19)
	v_cvt_pk_f32_fp8_e32 v[112:113], v76
	v_cvt_pk_f32_fp8_sdwa v[114:115], v76 src0_sel:WORD_1
	v_cvt_pk_f32_fp8_e32 v[116:117], v77
	v_cvt_pk_f32_fp8_sdwa v[118:119], v77 src0_sel:WORD_1
	v_cvt_pk_f32_fp8_e32 v[120:121], v78
	v_cvt_pk_f32_fp8_sdwa v[122:123], v78 src0_sel:WORD_1
	v_cvt_pk_f32_fp8_e32 v[124:125], v79
	v_cvt_pk_f32_fp8_sdwa v[126:127], v79 src0_sel:WORD_1
	global_load_dwordx4 v[76:79], v23, s[40:41]
	v_pk_mul_f32 v[142:143], v[112:113], v[0:1]
	v_pk_mul_f32 v[144:145], v[114:115], v[2:3]
	v_pk_fma_f32 v[142:143], v[116:117], v[4:5], v[142:143]
	v_pk_fma_f32 v[144:145], v[118:119], v[6:7], v[144:145]
	v_pk_fma_f32 v[142:143], v[120:121], v[8:9], v[142:143]
	v_pk_fma_f32 v[144:145], v[122:123], v[10:11], v[144:145]
	v_pk_fma_f32 v[142:143], v[124:125], v[12:13], v[142:143]
	v_pk_fma_f32 v[144:145], v[126:127], v[14:15], v[144:145]
	s_nop 0
	v_pk_add_f32 v[142:143], v[142:143], v[144:145]
	s_nop 0
	v_add_f32_e32 v146, v142, v143
	s_nop 1
	v_add_f32_dpp v146, v146, v146 quad_perm:[1,0,3,2] row_mask:0xf bank_mask:0xf
	s_nop 1
	v_add_f32_dpp v146, v146, v146 quad_perm:[2,3,0,1] row_mask:0xf bank_mask:0xf
	s_nop 1
	v_add_f32_dpp v146, v146, v146 row_half_mirror row_mask:0xf bank_mask:0xf
	v_cndmask_b32_e64 v139, v139, v146, s[18:19]
	s_waitcnt vmcnt(19)
	v_cvt_pk_f32_fp8_e32 v[112:113], v80
	v_cvt_pk_f32_fp8_sdwa v[114:115], v80 src0_sel:WORD_1
	v_cvt_pk_f32_fp8_e32 v[116:117], v81
	v_cvt_pk_f32_fp8_sdwa v[118:119], v81 src0_sel:WORD_1
	v_cvt_pk_f32_fp8_e32 v[120:121], v82
	v_cvt_pk_f32_fp8_sdwa v[122:123], v82 src0_sel:WORD_1
	v_cvt_pk_f32_fp8_e32 v[124:125], v83
	v_cvt_pk_f32_fp8_sdwa v[126:127], v83 src0_sel:WORD_1
	global_load_dwordx4 v[80:83], v24, s[40:41]
	v_pk_mul_f32 v[142:143], v[112:113], v[0:1]
	v_pk_mul_f32 v[144:145], v[114:115], v[2:3]
	v_pk_fma_f32 v[142:143], v[116:117], v[4:5], v[142:143]
	v_pk_fma_f32 v[144:145], v[118:119], v[6:7], v[144:145]
	v_pk_fma_f32 v[142:143], v[120:121], v[8:9], v[142:143]
	v_pk_fma_f32 v[144:145], v[122:123], v[10:11], v[144:145]
	v_pk_fma_f32 v[142:143], v[124:125], v[12:13], v[142:143]
	v_pk_fma_f32 v[144:145], v[126:127], v[14:15], v[144:145]
	s_nop 0
	v_pk_add_f32 v[142:143], v[142:143], v[144:145]
	s_nop 0
	v_add_f32_e32 v146, v142, v143
	s_nop 1
	v_add_f32_dpp v146, v146, v146 quad_perm:[1,0,3,2] row_mask:0xf bank_mask:0xf
	s_nop 1
	v_add_f32_dpp v146, v146, v146 quad_perm:[2,3,0,1] row_mask:0xf bank_mask:0xf
	s_nop 1
	v_add_f32_dpp v146, v146, v146 row_half_mirror row_mask:0xf bank_mask:0xf
	v_cndmask_b32_e64 v140, v140, v146, s[4:5]
	s_waitcnt vmcnt(19)
	v_cvt_pk_f32_fp8_e32 v[112:113], v84
	v_cvt_pk_f32_fp8_sdwa v[114:115], v84 src0_sel:WORD_1
	v_cvt_pk_f32_fp8_e32 v[116:117], v85
	v_cvt_pk_f32_fp8_sdwa v[118:119], v85 src0_sel:WORD_1
	v_cvt_pk_f32_fp8_e32 v[120:121], v86
	v_cvt_pk_f32_fp8_sdwa v[122:123], v86 src0_sel:WORD_1
	v_cvt_pk_f32_fp8_e32 v[124:125], v87
	v_cvt_pk_f32_fp8_sdwa v[126:127], v87 src0_sel:WORD_1
	global_load_dwordx4 v[84:87], v25, s[40:41]
	v_pk_mul_f32 v[142:143], v[112:113], v[0:1]
	v_pk_mul_f32 v[144:145], v[114:115], v[2:3]
	v_pk_fma_f32 v[142:143], v[116:117], v[4:5], v[142:143]
	v_pk_fma_f32 v[144:145], v[118:119], v[6:7], v[144:145]
	v_pk_fma_f32 v[142:143], v[120:121], v[8:9], v[142:143]
	v_pk_fma_f32 v[144:145], v[122:123], v[10:11], v[144:145]
	v_pk_fma_f32 v[142:143], v[124:125], v[12:13], v[142:143]
	v_pk_fma_f32 v[144:145], v[126:127], v[14:15], v[144:145]
	s_nop 0
	v_pk_add_f32 v[142:143], v[142:143], v[144:145]
	s_nop 0
	v_add_f32_e32 v146, v142, v143
	s_nop 1
	v_add_f32_dpp v146, v146, v146 quad_perm:[1,0,3,2] row_mask:0xf bank_mask:0xf
	s_nop 1
	v_add_f32_dpp v146, v146, v146 quad_perm:[2,3,0,1] row_mask:0xf bank_mask:0xf
	s_nop 1
	v_add_f32_dpp v146, v146, v146 row_half_mirror row_mask:0xf bank_mask:0xf
	v_cndmask_b32_e64 v140, v140, v146, s[6:7]
	s_waitcnt vmcnt(19)
	v_cvt_pk_f32_fp8_e32 v[112:113], v88
	v_cvt_pk_f32_fp8_sdwa v[114:115], v88 src0_sel:WORD_1
	v_cvt_pk_f32_fp8_e32 v[116:117], v89
	v_cvt_pk_f32_fp8_sdwa v[118:119], v89 src0_sel:WORD_1
	v_cvt_pk_f32_fp8_e32 v[120:121], v90
	v_cvt_pk_f32_fp8_sdwa v[122:123], v90 src0_sel:WORD_1
	v_cvt_pk_f32_fp8_e32 v[124:125], v91
	v_cvt_pk_f32_fp8_sdwa v[126:127], v91 src0_sel:WORD_1
	global_load_dwordx4 v[88:91], v26, s[40:41]
	v_pk_mul_f32 v[142:143], v[112:113], v[0:1]
	v_pk_mul_f32 v[144:145], v[114:115], v[2:3]
	v_pk_fma_f32 v[142:143], v[116:117], v[4:5], v[142:143]
	v_pk_fma_f32 v[144:145], v[118:119], v[6:7], v[144:145]
	v_pk_fma_f32 v[142:143], v[120:121], v[8:9], v[142:143]
	v_pk_fma_f32 v[144:145], v[122:123], v[10:11], v[144:145]
	v_pk_fma_f32 v[142:143], v[124:125], v[12:13], v[142:143]
	v_pk_fma_f32 v[144:145], v[126:127], v[14:15], v[144:145]
	s_nop 0
	v_pk_add_f32 v[142:143], v[142:143], v[144:145]
	s_nop 0
	v_add_f32_e32 v146, v142, v143
	s_nop 1
	v_add_f32_dpp v146, v146, v146 quad_perm:[1,0,3,2] row_mask:0xf bank_mask:0xf
	s_nop 1
	v_add_f32_dpp v146, v146, v146 quad_perm:[2,3,0,1] row_mask:0xf bank_mask:0xf
	s_nop 1
	v_add_f32_dpp v146, v146, v146 row_half_mirror row_mask:0xf bank_mask:0xf
	v_cndmask_b32_e64 v140, v140, v146, s[8:9]
	s_waitcnt vmcnt(19)
	v_cvt_pk_f32_fp8_e32 v[112:113], v92
	v_cvt_pk_f32_fp8_sdwa v[114:115], v92 src0_sel:WORD_1
	v_cvt_pk_f32_fp8_e32 v[116:117], v93
	v_cvt_pk_f32_fp8_sdwa v[118:119], v93 src0_sel:WORD_1
	v_cvt_pk_f32_fp8_e32 v[120:121], v94
	v_cvt_pk_f32_fp8_sdwa v[122:123], v94 src0_sel:WORD_1
	v_cvt_pk_f32_fp8_e32 v[124:125], v95
	v_cvt_pk_f32_fp8_sdwa v[126:127], v95 src0_sel:WORD_1
	global_load_dwordx4 v[92:95], v27, s[40:41]
	v_pk_mul_f32 v[142:143], v[112:113], v[0:1]
	v_pk_mul_f32 v[144:145], v[114:115], v[2:3]
	v_pk_fma_f32 v[142:143], v[116:117], v[4:5], v[142:143]
	v_pk_fma_f32 v[144:145], v[118:119], v[6:7], v[144:145]
	v_pk_fma_f32 v[142:143], v[120:121], v[8:9], v[142:143]
	v_pk_fma_f32 v[144:145], v[122:123], v[10:11], v[144:145]
	v_pk_fma_f32 v[142:143], v[124:125], v[12:13], v[142:143]
	v_pk_fma_f32 v[144:145], v[126:127], v[14:15], v[144:145]
	s_nop 0
	v_pk_add_f32 v[142:143], v[142:143], v[144:145]
	s_nop 0
	v_add_f32_e32 v146, v142, v143
	s_nop 1
	v_add_f32_dpp v146, v146, v146 quad_perm:[1,0,3,2] row_mask:0xf bank_mask:0xf
	s_nop 1
	v_add_f32_dpp v146, v146, v146 quad_perm:[2,3,0,1] row_mask:0xf bank_mask:0xf
	s_nop 1
	v_add_f32_dpp v146, v146, v146 row_half_mirror row_mask:0xf bank_mask:0xf
	v_cndmask_b32_e64 v140, v140, v146, s[10:11]
	s_waitcnt vmcnt(19)
	v_cvt_pk_f32_fp8_e32 v[112:113], v96
	v_cvt_pk_f32_fp8_sdwa v[114:115], v96 src0_sel:WORD_1
	v_cvt_pk_f32_fp8_e32 v[116:117], v97
	v_cvt_pk_f32_fp8_sdwa v[118:119], v97 src0_sel:WORD_1
	v_cvt_pk_f32_fp8_e32 v[120:121], v98
	v_cvt_pk_f32_fp8_sdwa v[122:123], v98 src0_sel:WORD_1
	v_cvt_pk_f32_fp8_e32 v[124:125], v99
	v_cvt_pk_f32_fp8_sdwa v[126:127], v99 src0_sel:WORD_1
	global_load_dwordx4 v[96:99], v28, s[40:41]
	v_pk_mul_f32 v[142:143], v[112:113], v[0:1]
	v_pk_mul_f32 v[144:145], v[114:115], v[2:3]
	v_pk_fma_f32 v[142:143], v[116:117], v[4:5], v[142:143]
	v_pk_fma_f32 v[144:145], v[118:119], v[6:7], v[144:145]
	v_pk_fma_f32 v[142:143], v[120:121], v[8:9], v[142:143]
	v_pk_fma_f32 v[144:145], v[122:123], v[10:11], v[144:145]
	v_pk_fma_f32 v[142:143], v[124:125], v[12:13], v[142:143]
	v_pk_fma_f32 v[144:145], v[126:127], v[14:15], v[144:145]
	s_nop 0
	v_pk_add_f32 v[142:143], v[142:143], v[144:145]
	s_nop 0
	v_add_f32_e32 v146, v142, v143
	s_nop 1
	v_add_f32_dpp v146, v146, v146 quad_perm:[1,0,3,2] row_mask:0xf bank_mask:0xf
	s_nop 1
	v_add_f32_dpp v146, v146, v146 quad_perm:[2,3,0,1] row_mask:0xf bank_mask:0xf
	s_nop 1
	v_add_f32_dpp v146, v146, v146 row_half_mirror row_mask:0xf bank_mask:0xf
	v_cndmask_b32_e64 v140, v140, v146, s[12:13]
	s_waitcnt vmcnt(19)
	v_cvt_pk_f32_fp8_e32 v[112:113], v100
	v_cvt_pk_f32_fp8_sdwa v[114:115], v100 src0_sel:WORD_1
	v_cvt_pk_f32_fp8_e32 v[116:117], v101
	v_cvt_pk_f32_fp8_sdwa v[118:119], v101 src0_sel:WORD_1
	v_cvt_pk_f32_fp8_e32 v[120:121], v102
	v_cvt_pk_f32_fp8_sdwa v[122:123], v102 src0_sel:WORD_1
	v_cvt_pk_f32_fp8_e32 v[124:125], v103
	v_cvt_pk_f32_fp8_sdwa v[126:127], v103 src0_sel:WORD_1
	global_load_dwordx4 v[100:103], v29, s[40:41]
	v_pk_mul_f32 v[142:143], v[112:113], v[0:1]
	v_pk_mul_f32 v[144:145], v[114:115], v[2:3]
	v_pk_fma_f32 v[142:143], v[116:117], v[4:5], v[142:143]
	v_pk_fma_f32 v[144:145], v[118:119], v[6:7], v[144:145]
	v_pk_fma_f32 v[142:143], v[120:121], v[8:9], v[142:143]
	v_pk_fma_f32 v[144:145], v[122:123], v[10:11], v[144:145]
	v_pk_fma_f32 v[142:143], v[124:125], v[12:13], v[142:143]
	v_pk_fma_f32 v[144:145], v[126:127], v[14:15], v[144:145]
	s_nop 0
	v_pk_add_f32 v[142:143], v[142:143], v[144:145]
	s_nop 0
	v_add_f32_e32 v146, v142, v143
	s_nop 1
	v_add_f32_dpp v146, v146, v146 quad_perm:[1,0,3,2] row_mask:0xf bank_mask:0xf
	s_nop 1
	v_add_f32_dpp v146, v146, v146 quad_perm:[2,3,0,1] row_mask:0xf bank_mask:0xf
	s_nop 1
	v_add_f32_dpp v146, v146, v146 row_half_mirror row_mask:0xf bank_mask:0xf
	v_cndmask_b32_e64 v140, v140, v146, s[14:15]
	s_waitcnt vmcnt(19)
	v_cvt_pk_f32_fp8_e32 v[112:113], v104
	v_cvt_pk_f32_fp8_sdwa v[114:115], v104 src0_sel:WORD_1
	v_cvt_pk_f32_fp8_e32 v[116:117], v105
	v_cvt_pk_f32_fp8_sdwa v[118:119], v105 src0_sel:WORD_1
	v_cvt_pk_f32_fp8_e32 v[120:121], v106
	v_cvt_pk_f32_fp8_sdwa v[122:123], v106 src0_sel:WORD_1
	v_cvt_pk_f32_fp8_e32 v[124:125], v107
	v_cvt_pk_f32_fp8_sdwa v[126:127], v107 src0_sel:WORD_1
	global_load_dwordx4 v[104:107], v30, s[40:41]
	v_pk_mul_f32 v[142:143], v[112:113], v[0:1]
	v_pk_mul_f32 v[144:145], v[114:115], v[2:3]
	v_pk_fma_f32 v[142:143], v[116:117], v[4:5], v[142:143]
	v_pk_fma_f32 v[144:145], v[118:119], v[6:7], v[144:145]
	v_pk_fma_f32 v[142:143], v[120:121], v[8:9], v[142:143]
	v_pk_fma_f32 v[144:145], v[122:123], v[10:11], v[144:145]
	v_pk_fma_f32 v[142:143], v[124:125], v[12:13], v[142:143]
	v_pk_fma_f32 v[144:145], v[126:127], v[14:15], v[144:145]
	s_nop 0
	v_pk_add_f32 v[142:143], v[142:143], v[144:145]
	s_nop 0
	v_add_f32_e32 v146, v142, v143
	s_nop 1
	v_add_f32_dpp v146, v146, v146 quad_perm:[1,0,3,2] row_mask:0xf bank_mask:0xf
	s_nop 1
	v_add_f32_dpp v146, v146, v146 quad_perm:[2,3,0,1] row_mask:0xf bank_mask:0xf
	s_nop 1
	v_add_f32_dpp v146, v146, v146 row_half_mirror row_mask:0xf bank_mask:0xf
	v_cndmask_b32_e64 v140, v140, v146, s[16:17]
	s_waitcnt vmcnt(19)
	v_cvt_pk_f32_fp8_e32 v[112:113], v108
	v_cvt_pk_f32_fp8_sdwa v[114:115], v108 src0_sel:WORD_1
	v_cvt_pk_f32_fp8_e32 v[116:117], v109
	v_cvt_pk_f32_fp8_sdwa v[118:119], v109 src0_sel:WORD_1
	v_cvt_pk_f32_fp8_e32 v[120:121], v110
	v_cvt_pk_f32_fp8_sdwa v[122:123], v110 src0_sel:WORD_1
	v_cvt_pk_f32_fp8_e32 v[124:125], v111
	v_cvt_pk_f32_fp8_sdwa v[126:127], v111 src0_sel:WORD_1
	global_load_dwordx4 v[108:111], v31, s[40:41]
	v_pk_mul_f32 v[142:143], v[112:113], v[0:1]
	v_pk_mul_f32 v[144:145], v[114:115], v[2:3]
	v_pk_fma_f32 v[142:143], v[116:117], v[4:5], v[142:143]
	v_pk_fma_f32 v[144:145], v[118:119], v[6:7], v[144:145]
	v_pk_fma_f32 v[142:143], v[120:121], v[8:9], v[142:143]
	v_pk_fma_f32 v[144:145], v[122:123], v[10:11], v[144:145]
	v_pk_fma_f32 v[142:143], v[124:125], v[12:13], v[142:143]
	v_pk_fma_f32 v[144:145], v[126:127], v[14:15], v[144:145]
	s_nop 0
	v_pk_add_f32 v[142:143], v[142:143], v[144:145]
	s_nop 0
	v_add_f32_e32 v146, v142, v143
	s_nop 1
	v_add_f32_dpp v146, v146, v146 quad_perm:[1,0,3,2] row_mask:0xf bank_mask:0xf
	s_nop 1
	v_add_f32_dpp v146, v146, v146 quad_perm:[2,3,0,1] row_mask:0xf bank_mask:0xf
	s_nop 1
	v_add_f32_dpp v146, v146, v146 row_half_mirror row_mask:0xf bank_mask:0xf
	v_cndmask_b32_e64 v140, v140, v146, s[18:19]
	s_lshl_b32 s98, s54, 9
	s_add_u32 s52, s92, s98
	s_addc_u32 s53, s93, 0
	global_store_dword v160, v139, s[52:53]
	global_store_dword v160, v140, s[52:53] offset:256
	s_waitcnt vmcnt(16)
	ds_bpermute_b32 v16, v130, v150
	ds_bpermute_b32 v17, v131, v150
	ds_bpermute_b32 v18, v132, v150
	ds_bpermute_b32 v19, v133, v150
	ds_bpermute_b32 v20, v134, v150
	ds_bpermute_b32 v21, v135, v150
	ds_bpermute_b32 v22, v136, v150
	ds_bpermute_b32 v23, v137, v150
	ds_bpermute_b32 v24, v130, v151
	ds_bpermute_b32 v25, v131, v151
	ds_bpermute_b32 v26, v132, v151
	ds_bpermute_b32 v27, v133, v151
	ds_bpermute_b32 v28, v134, v151
	ds_bpermute_b32 v29, v135, v151
	ds_bpermute_b32 v30, v136, v151
	ds_bpermute_b32 v31, v137, v151
	v_lshlrev_b32_e32 v0, 16, v152
	v_and_b32_e32 v1, 0xffff0000, v152
	v_lshlrev_b32_e32 v2, 16, v153
	v_and_b32_e32 v3, 0xffff0000, v153
	v_lshlrev_b32_e32 v4, 16, v154
	v_and_b32_e32 v5, 0xffff0000, v154
	v_lshlrev_b32_e32 v6, 16, v155
	v_and_b32_e32 v7, 0xffff0000, v155
	v_lshlrev_b32_e32 v8, 16, v156
	v_and_b32_e32 v9, 0xffff0000, v156
	v_lshlrev_b32_e32 v10, 16, v157
	v_and_b32_e32 v11, 0xffff0000, v157
	v_lshlrev_b32_e32 v12, 16, v158
	v_and_b32_e32 v13, 0xffff0000, v158
	v_lshlrev_b32_e32 v14, 16, v159
	v_and_b32_e32 v15, 0xffff0000, v159
	s_waitcnt lgkmcnt(0)
	v_lshl_add_u32 v16, v16, 10, v138
	v_lshl_add_u32 v17, v17, 10, v138
	v_lshl_add_u32 v18, v18, 10, v138
	v_lshl_add_u32 v19, v19, 10, v138
	v_lshl_add_u32 v20, v20, 10, v138
	v_lshl_add_u32 v21, v21, 10, v138
	v_lshl_add_u32 v22, v22, 10, v138
	v_lshl_add_u32 v23, v23, 10, v138
	v_lshl_add_u32 v24, v24, 10, v138
	v_lshl_add_u32 v25, v25, 10, v138
	v_lshl_add_u32 v26, v26, 10, v138
	v_lshl_add_u32 v27, v27, 10, v138
	v_lshl_add_u32 v28, v28, 10, v138
	v_lshl_add_u32 v29, v29, 10, v138
	v_lshl_add_u32 v30, v30, 10, v138
	v_lshl_add_u32 v31, v31, 10, v138
	s_mov_b32 s54, s99
	s_cmp_lt_u32 s54, 0x4200
	s_cbranch_scc1 .Lgy_Atok_7

.Lgy_B_2:
	v_lshrrev_b32_e32 v142, 6, v162
	v_readlane_b32 s2, v242, 0
	v_readlane_b32 s59, v241, 24
	v_readfirstlane_b32 s29, v142
	s_lshl_b32 s2, s2, 2
	s_add_u32 s54, s2, s29
	s_load_dwordx4 s[88:91], s[0:1], 0x1a8
	s_load_dwordx2 s[92:93], s[0:1], 0x130
	v_readlane_b32 s44, v240, 6
	v_readlane_b32 s45, v240, 7
	v_lshlrev_b32_e32 v160, 2, v168
	s_waitcnt lgkmcnt(0)
	s_add_u32 s50, s44, 0x10000
	s_addc_u32 s51, s45, 0
	s_cmp_lt_u32 s54, 0x4200
	s_cbranch_scc0 .Lgy_Bdone_9
.Lgy_Btok_8:
	s_lshl_b32 s98, s54, 9
	s_add_u32 s52, s88, s98
	s_addc_u32 s53, s89, 0
	global_load_dword v0, v160, s[52:53]
	global_load_dword v1, v160, s[52:53] offset:256
	s_add_u32 s46, s90, s98
	s_addc_u32 s47, s91, 0
	global_load_dword v2, v160, s[46:47]
	global_load_dword v3, v160, s[46:47] offset:256
	s_add_u32 s52, s92, s98
	s_addc_u32 s53, s93, 0
	global_load_dword v8, v160, s[52:53]
	global_load_dword v9, v160, s[52:53] offset:256
	s_add_u32 s52, s52, 0x840000
	s_addc_u32 s53, s53, 0
	global_load_dword v10, v160, s[52:53]
	global_load_dword v11, v160, s[52:53] offset:256
	s_add_u32 s52, s52, 0x840000
	s_addc_u32 s53, s53, 0
	global_load_dword v12, v160, s[52:53]
	global_load_dword v13, v160, s[52:53] offset:256
	s_add_u32 s52, s52, 0x840000
	s_addc_u32 s53, s53, 0
	global_load_dword v14, v160, s[52:53]
	global_load_dword v15, v160, s[52:53] offset:256
	s_add_u32 s52, s52, 0x840000
	s_addc_u32 s53, s53, 0
	global_load_dword v16, v160, s[52:53]
	global_load_dword v17, v160, s[52:53] offset:256
	s_add_u32 s52, s52, 0x840000
	s_addc_u32 s53, s53, 0
	global_load_dword v18, v160, s[52:53]
	global_load_dword v19, v160, s[52:53] offset:256
	s_add_u32 s52, s52, 0x840000
	s_addc_u32 s53, s53, 0
	global_load_dword v20, v160, s[52:53]
	global_load_dword v21, v160, s[52:53] offset:256
	s_add_u32 s52, s52, 0x840000
	s_addc_u32 s53, s53, 0
	global_load_dword v22, v160, s[52:53]
	global_load_dword v23, v160, s[52:53] offset:256
	s_waitcnt vmcnt(18)
	v_lshlrev_b32_e32 v142, 2, v0
	v_lshlrev_b32_e32 v143, 2, v1
	global_load_dword v4, v142, s[44:45]
	global_load_dword v6, v142, s[50:51]
	global_load_dword v5, v143, s[44:45]
	global_load_dword v7, v143, s[50:51]
	s_waitcnt vmcnt(4)
	v_add_f32_e32 v8, v8, v10
	v_add_f32_e32 v8, v8, v12
	v_add_f32_e32 v8, v8, v14
	v_add_f32_e32 v8, v8, v16
	v_add_f32_e32 v8, v8, v18
	v_add_f32_e32 v8, v8, v20
	v_add_f32_e32 v8, v8, v22
	v_add_f32_e32 v9, v9, v11
	v_add_f32_e32 v9, v9, v13
	v_add_f32_e32 v9, v9, v15
	v_add_f32_e32 v9, v9, v17
	v_add_f32_e32 v9, v9, v19
	v_add_f32_e32 v9, v9, v21
	v_add_f32_e32 v9, v9, v23
	s_waitcnt vmcnt(0)
	v_mul_f32_e32 v144, v4, v8
	v_mul_f32_e32 v145, 0x3d372713, v144
	v_mul_f32_e32 v145, v144, v145
	v_fma_f32 v145, v144, v145, v144
	v_mul_f32_e32 v145, 0x3f4c422a, v145
	v_mul_f32_e32 v145, -2.0, v145
	v_mul_f32_e32 v145, 0x3fb8aa3b, v145
	v_exp_f32_e32 v145, v145
	v_mul_f32_e32 v2, v2, v6
	v_add_f32_e32 v145, 1.0, v145
	v_rcp_f32_e32 v145, v145
	s_nop 0
	v_mul_f32_e32 v144, v144, v145
	v_mul_f32_e32 v2, v2, v144
	v_mul_f32_e32 v146, v5, v9
	v_mul_f32_e32 v147, 0x3d372713, v146
	v_mul_f32_e32 v147, v146, v147
	v_fma_f32 v147, v146, v147, v146
	v_mul_f32_e32 v147, 0x3f4c422a, v147
	v_mul_f32_e32 v147, -2.0, v147
	v_mul_f32_e32 v147, 0x3fb8aa3b, v147
	v_exp_f32_e32 v147, v147
	v_mul_f32_e32 v3, v3, v7
	v_add_f32_e32 v147, 1.0, v147
	v_rcp_f32_e32 v147, v147
	s_nop 0
	v_mul_f32_e32 v146, v146, v147
	v_mul_f32_e32 v3, v3, v146
	global_store_dword v160, v2, s[46:47]
	global_store_dword v160, v3, s[46:47] offset:256
	s_add_u32 s54, s54, s59
	s_cmp_lt_u32 s54, 0x4200
	s_cbranch_scc1 .Lgy_Btok_8

.Lgy_C_3:
	v_lshrrev_b32_e32 v142, 6, v162
	v_readlane_b32 s2, v242, 0
	v_readlane_b32 s59, v241, 24
	v_readfirstlane_b32 s29, v142
	s_and_b32 s28, s2, 7
	s_lshr_b32 s2, s2, 3
	s_lshl_b32 s2, s2, 2
	s_add_u32 s54, s2, s29
	s_lshr_b32 s59, s59, 3
	s_load_dwordx2 s[88:89], s[0:1], 0x1a8
	s_load_dwordx2 s[90:91], s[0:1], 0x1b0
	s_load_dwordx2 s[92:93], s[0:1], 0x120
	s_load_dwordx2 s[94:95], s[0:1], 0xc8
	v_readlane_b32 s40, v240, 10
	v_readlane_b32 s41, v240, 11
	v_and_b32_e32 v142, 7, v168
	v_lshlrev_b32_e32 v160, 2, v168
	s_lshl_b32 s32, s28, 7
	v_lshl_add_u32 v138, v142, 4, s32
	v_and_b32_e32 v143, 0xf8, v168
	v_add_u32_e32 v130, 0, v143
	v_add_u32_e32 v131, 1, v143
	v_add_u32_e32 v132, 2, v143
	v_add_u32_e32 v133, 3, v143
	v_add_u32_e32 v134, 4, v143
	v_add_u32_e32 v135, 5, v143
	v_add_u32_e32 v136, 6, v143
	v_add_u32_e32 v137, 7, v143
	v_lshlrev_b32_e32 v130, 2, v130
	v_lshlrev_b32_e32 v131, 2, v131
	v_lshlrev_b32_e32 v132, 2, v132
	v_lshlrev_b32_e32 v133, 2, v133
	v_lshlrev_b32_e32 v134, 2, v134
	v_lshlrev_b32_e32 v135, 2, v135
	v_lshlrev_b32_e32 v136, 2, v136
	v_lshlrev_b32_e32 v137, 2, v137
	v_lshrrev_b32_e32 v144, 3, v168
	v_lshlrev_b32_e32 v144, 3, v144
	s_lshl_b32 s32, s28, 9
	v_lshl_add_u32 v188, v142, 6, s32
	v_add_u32_e32 v188, v188, v144
	s_mov_b32 s16, 0x3fd744fd
	s_waitcnt lgkmcnt(0)
	s_nop 4
	s_cmp_lt_u32 s54, 0x4200
	s_cbranch_scc0 .Lgy_Cdone_10
	s_min_u32 s98, s54, 0x41ff
	s_lshl_b32 s98, s98, 9
	s_add_u32 s52, s88, s98
	s_addc_u32 s53, s89, 0
	global_load_dword v144, v160, s[52:53]
	global_load_dword v145, v160, s[52:53] offset:256
	s_add_u32 s99, s54, s59
	s_min_u32 s98, s99, 0x41ff
	s_lshl_b32 s98, s98, 9
	s_add_u32 s52, s88, s98
	s_addc_u32 s53, s89, 0
	global_load_dword v150, v160, s[52:53]
	global_load_dword v151, v160, s[52:53] offset:256
	s_min_u32 s98, s54, 0x41ff
	s_lshl_b32 s98, s98, 9
	s_add_u32 s52, s90, s98
	s_addc_u32 s53, s91, 0
	global_load_dword v194, v160, s[52:53]
	global_load_dword v195, v160, s[52:53] offset:256
	s_waitcnt vmcnt(0)
	ds_bpermute_b32 v16, v130, v144
	ds_bpermute_b32 v17, v131, v144
	ds_bpermute_b32 v18, v132, v144
	ds_bpermute_b32 v19, v133, v144
	ds_bpermute_b32 v20, v134, v144
	ds_bpermute_b32 v21, v135, v144
	ds_bpermute_b32 v22, v136, v144
	ds_bpermute_b32 v23, v137, v144
	ds_bpermute_b32 v24, v130, v145
	ds_bpermute_b32 v25, v131, v145
	ds_bpermute_b32 v26, v132, v145
	ds_bpermute_b32 v27, v133, v145
	ds_bpermute_b32 v28, v134, v145
	ds_bpermute_b32 v29, v135, v145
	ds_bpermute_b32 v30, v136, v145
	ds_bpermute_b32 v31, v137, v145
	s_waitcnt lgkmcnt(0)
	v_lshl_add_u32 v16, v16, 10, v138
	v_lshl_add_u32 v17, v17, 10, v138
	v_lshl_add_u32 v18, v18, 10, v138
	v_lshl_add_u32 v19, v19, 10, v138
	v_lshl_add_u32 v20, v20, 10, v138
	v_lshl_add_u32 v21, v21, 10, v138
	v_lshl_add_u32 v22, v22, 10, v138
	v_lshl_add_u32 v23, v23, 10, v138
	v_lshl_add_u32 v24, v24, 10, v138
	v_lshl_add_u32 v25, v25, 10, v138
	v_lshl_add_u32 v26, v26, 10, v138
	v_lshl_add_u32 v27, v27, 10, v138
	v_lshl_add_u32 v28, v28, 10, v138
	v_lshl_add_u32 v29, v29, 10, v138
	v_lshl_add_u32 v30, v30, 10, v138
	v_lshl_add_u32 v31, v31, 10, v138
	global_load_dwordx4 v[48:51], v16, s[40:41]
	global_load_dwordx4 v[52:55], v17, s[40:41]
	global_load_dwordx4 v[56:59], v18, s[40:41]
	global_load_dwordx4 v[60:63], v19, s[40:41]
	global_load_dwordx4 v[64:67], v20, s[40:41]
	global_load_dwordx4 v[68:71], v21, s[40:41]
	global_load_dwordx4 v[72:75], v22, s[40:41]
	global_load_dwordx4 v[76:79], v23, s[40:41]
	global_load_dwordx4 v[80:83], v24, s[40:41]
	global_load_dwordx4 v[84:87], v25, s[40:41]
	global_load_dwordx4 v[88:91], v26, s[40:41]
	global_load_dwordx4 v[92:95], v27, s[40:41]
	global_load_dwordx4 v[96:99], v28, s[40:41]
	global_load_dwordx4 v[100:103], v29, s[40:41]
	global_load_dwordx4 v[104:107], v30, s[40:41]
	global_load_dwordx4 v[108:111], v31, s[40:41]
	global_load_dword v146, v160, s[52:53]
	ds_bpermute_b32 v16, v130, v150
	ds_bpermute_b32 v17, v131, v150
	ds_bpermute_b32 v18, v132, v150
	ds_bpermute_b32 v19, v133, v150
	ds_bpermute_b32 v20, v134, v150
	ds_bpermute_b32 v21, v135, v150
	ds_bpermute_b32 v22, v136, v150
	ds_bpermute_b32 v23, v137, v150
	ds_bpermute_b32 v24, v130, v151
	ds_bpermute_b32 v25, v131, v151
	ds_bpermute_b32 v26, v132, v151
	ds_bpermute_b32 v27, v133, v151
	ds_bpermute_b32 v28, v134, v151
	ds_bpermute_b32 v29, v135, v151
	ds_bpermute_b32 v30, v136, v151
	ds_bpermute_b32 v31, v137, v151
	s_waitcnt lgkmcnt(0)
	v_lshl_add_u32 v16, v16, 10, v138
	v_lshl_add_u32 v17, v17, 10, v138
	v_lshl_add_u32 v18, v18, 10, v138
	v_lshl_add_u32 v19, v19, 10, v138
	v_lshl_add_u32 v20, v20, 10, v138
	v_lshl_add_u32 v21, v21, 10, v138
	v_lshl_add_u32 v22, v22, 10, v138
	v_lshl_add_u32 v23, v23, 10, v138
	v_lshl_add_u32 v24, v24, 10, v138
	v_lshl_add_u32 v25, v25, 10, v138
	v_lshl_add_u32 v26, v26, 10, v138
	v_lshl_add_u32 v27, v27, 10, v138
	v_lshl_add_u32 v28, v28, 10, v138
	v_lshl_add_u32 v29, v29, 10, v138
	v_lshl_add_u32 v30, v30, 10, v138
	v_lshl_add_u32 v31, v31, 10, v138
	ds_bpermute_b32 v32, v130, v194
	ds_bpermute_b32 v33, v131, v194
	ds_bpermute_b32 v34, v132, v194
	ds_bpermute_b32 v35, v133, v194
	ds_bpermute_b32 v36, v134, v194
	ds_bpermute_b32 v37, v135, v194
	ds_bpermute_b32 v38, v136, v194
	ds_bpermute_b32 v39, v137, v194
	ds_bpermute_b32 v40, v130, v195
	ds_bpermute_b32 v41, v131, v195
	ds_bpermute_b32 v42, v132, v195
	ds_bpermute_b32 v43, v133, v195
	ds_bpermute_b32 v44, v134, v195
	ds_bpermute_b32 v45, v135, v195
	ds_bpermute_b32 v46, v136, v195
	ds_bpermute_b32 v47, v137, v195
.Lgy_Ctok_11:
	s_add_u32 s99, s54, s59
	s_add_u32 s96, s99, s59
	s_min_u32 s98, s96, 0x41ff
	s_lshl_b32 s98, s98, 9
	s_add_u32 s52, s88, s98
	s_addc_u32 s53, s89, 0
	global_load_dword v150, v160, s[52:53]
	global_load_dword v151, v160, s[52:53] offset:256
	s_min_u32 s98, s99, 0x41ff
	s_lshl_b32 s98, s98, 9
	s_add_u32 s52, s90, s98
	s_addc_u32 s53, s91, 0
	global_load_dword v194, v160, s[52:53]
	global_load_dword v195, v160, s[52:53] offset:256
	s_lshl_b32 s98, s54, 12
	s_add_u32 s52, s70, s98
	s_addc_u32 s53, s71, 0
	global_load_dwordx2 v[190:191], v188, s[52:53]
	s_cmp_lt_u32 s54, 0x2000
	s_cselect_b32 s98, 0, 1
	s_cmp_lt_u32 s54, 0x4000
	s_cselect_b32 s98, s98, 2
	s_add_u32 s98, s98, s27
	s_mul_i32 s98, s98, 0x6000
	s_add_u32 s98, s98, 0x5000
	s_add_u32 s52, s94, s98
	s_addc_u32 s53, s95, 0
	global_load_dwordx2 v[192:193], v188, s[52:53]
	v_mov_b32_e32 v0, 0
	v_mov_b32_e32 v1, 0
	v_mov_b32_e32 v2, 0
	v_mov_b32_e32 v3, 0
	v_mov_b32_e32 v4, 0
	v_mov_b32_e32 v5, 0
	v_mov_b32_e32 v6, 0
	v_mov_b32_e32 v7, 0
	v_mov_b32_e32 v8, 0
	v_mov_b32_e32 v9, 0
	v_mov_b32_e32 v10, 0
	v_mov_b32_e32 v11, 0
	v_mov_b32_e32 v12, 0
	v_mov_b32_e32 v13, 0
	v_mov_b32_e32 v14, 0
	v_mov_b32_e32 v15, 0
	s_waitcnt lgkmcnt(0)
	s_waitcnt vmcnt(21)
	v_cvt_pk_f32_fp8_e32 v[112:113], v48
	v_cvt_pk_f32_fp8_sdwa v[114:115], v48 src0_sel:WORD_1
	v_cvt_pk_f32_fp8_e32 v[116:117], v49
	v_cvt_pk_f32_fp8_sdwa v[118:119], v49 src0_sel:WORD_1
	v_cvt_pk_f32_fp8_e32 v[120:121], v50
	v_cvt_pk_f32_fp8_sdwa v[122:123], v50 src0_sel:WORD_1
	v_cvt_pk_f32_fp8_e32 v[124:125], v51
	v_cvt_pk_f32_fp8_sdwa v[126:127], v51 src0_sel:WORD_1
	global_load_dwordx4 v[48:51], v16, s[40:41]
	v_pk_fma_f32 v[0:1], v[112:113], v[32:33], v[0:1] op_sel_hi:[1,0,1]
	v_pk_fma_f32 v[2:3], v[114:115], v[32:33], v[2:3] op_sel_hi:[1,0,1]
	v_pk_fma_f32 v[4:5], v[116:117], v[32:33], v[4:5] op_sel_hi:[1,0,1]
	v_pk_fma_f32 v[6:7], v[118:119], v[32:33], v[6:7] op_sel_hi:[1,0,1]
	v_pk_fma_f32 v[8:9], v[120:121], v[32:33], v[8:9] op_sel_hi:[1,0,1]
	v_pk_fma_f32 v[10:11], v[122:123], v[32:33], v[10:11] op_sel_hi:[1,0,1]
	v_pk_fma_f32 v[12:13], v[124:125], v[32:33], v[12:13] op_sel_hi:[1,0,1]
	v_pk_fma_f32 v[14:15], v[126:127], v[32:33], v[14:15] op_sel_hi:[1,0,1]
	s_waitcnt vmcnt(21)
	v_cvt_pk_f32_fp8_e32 v[112:113], v52
	v_cvt_pk_f32_fp8_sdwa v[114:115], v52 src0_sel:WORD_1
	v_cvt_pk_f32_fp8_e32 v[116:117], v53
	v_cvt_pk_f32_fp8_sdwa v[118:119], v53 src0_sel:WORD_1
	v_cvt_pk_f32_fp8_e32 v[120:121], v54
	v_cvt_pk_f32_fp8_sdwa v[122:123], v54 src0_sel:WORD_1
	v_cvt_pk_f32_fp8_e32 v[124:125], v55
	v_cvt_pk_f32_fp8_sdwa v[126:127], v55 src0_sel:WORD_1
	global_load_dwordx4 v[52:55], v17, s[40:41]
	v_pk_fma_f32 v[0:1], v[112:113], v[32:33], v[0:1] op_sel:[0,1,0] op_sel_hi:[1,1,1]
	v_pk_fma_f32 v[2:3], v[114:115], v[32:33], v[2:3] op_sel:[0,1,0] op_sel_hi:[1,1,1]
	v_pk_fma_f32 v[4:5], v[116:117], v[32:33], v[4:5] op_sel:[0,1,0] op_sel_hi:[1,1,1]
	v_pk_fma_f32 v[6:7], v[118:119], v[32:33], v[6:7] op_sel:[0,1,0] op_sel_hi:[1,1,1]
	v_pk_fma_f32 v[8:9], v[120:121], v[32:33], v[8:9] op_sel:[0,1,0] op_sel_hi:[1,1,1]
	v_pk_fma_f32 v[10:11], v[122:123], v[32:33], v[10:11] op_sel:[0,1,0] op_sel_hi:[1,1,1]
	v_pk_fma_f32 v[12:13], v[124:125], v[32:33], v[12:13] op_sel:[0,1,0] op_sel_hi:[1,1,1]
	v_pk_fma_f32 v[14:15], v[126:127], v[32:33], v[14:15] op_sel:[0,1,0] op_sel_hi:[1,1,1]
	s_waitcnt vmcnt(21)
	v_cvt_pk_f32_fp8_e32 v[112:113], v56
	v_cvt_pk_f32_fp8_sdwa v[114:115], v56 src0_sel:WORD_1
	v_cvt_pk_f32_fp8_e32 v[116:117], v57
	v_cvt_pk_f32_fp8_sdwa v[118:119], v57 src0_sel:WORD_1
	v_cvt_pk_f32_fp8_e32 v[120:121], v58
	v_cvt_pk_f32_fp8_sdwa v[122:123], v58 src0_sel:WORD_1
	v_cvt_pk_f32_fp8_e32 v[124:125], v59
	v_cvt_pk_f32_fp8_sdwa v[126:127], v59 src0_sel:WORD_1
	global_load_dwordx4 v[56:59], v18, s[40:41]
	v_pk_fma_f32 v[0:1], v[112:113], v[34:35], v[0:1] op_sel_hi:[1,0,1]
	v_pk_fma_f32 v[2:3], v[114:115], v[34:35], v[2:3] op_sel_hi:[1,0,1]
	v_pk_fma_f32 v[4:5], v[116:117], v[34:35], v[4:5] op_sel_hi:[1,0,1]
	v_pk_fma_f32 v[6:7], v[118:119], v[34:35], v[6:7] op_sel_hi:[1,0,1]
	v_pk_fma_f32 v[8:9], v[120:121], v[34:35], v[8:9] op_sel_hi:[1,0,1]
	v_pk_fma_f32 v[10:11], v[122:123], v[34:35], v[10:11] op_sel_hi:[1,0,1]
	v_pk_fma_f32 v[12:13], v[124:125], v[34:35], v[12:13] op_sel_hi:[1,0,1]
	v_pk_fma_f32 v[14:15], v[126:127], v[34:35], v[14:15] op_sel_hi:[1,0,1]
	s_waitcnt vmcnt(21)
	v_cvt_pk_f32_fp8_e32 v[112:113], v60
	v_cvt_pk_f32_fp8_sdwa v[114:115], v60 src0_sel:WORD_1
	v_cvt_pk_f32_fp8_e32 v[116:117], v61
	v_cvt_pk_f32_fp8_sdwa v[118:119], v61 src0_sel:WORD_1
	v_cvt_pk_f32_fp8_e32 v[120:121], v62
	v_cvt_pk_f32_fp8_sdwa v[122:123], v62 src0_sel:WORD_1
	v_cvt_pk_f32_fp8_e32 v[124:125], v63
	v_cvt_pk_f32_fp8_sdwa v[126:127], v63 src0_sel:WORD_1
	global_load_dwordx4 v[60:63], v19, s[40:41]
	v_pk_fma_f32 v[0:1], v[112:113], v[34:35], v[0:1] op_sel:[0,1,0] op_sel_hi:[1,1,1]
	v_pk_fma_f32 v[2:3], v[114:115], v[34:35], v[2:3] op_sel:[0,1,0] op_sel_hi:[1,1,1]
	v_pk_fma_f32 v[4:5], v[116:117], v[34:35], v[4:5] op_sel:[0,1,0] op_sel_hi:[1,1,1]
	v_pk_fma_f32 v[6:7], v[118:119], v[34:35], v[6:7] op_sel:[0,1,0] op_sel_hi:[1,1,1]
	v_pk_fma_f32 v[8:9], v[120:121], v[34:35], v[8:9] op_sel:[0,1,0] op_sel_hi:[1,1,1]
	v_pk_fma_f32 v[10:11], v[122:123], v[34:35], v[10:11] op_sel:[0,1,0] op_sel_hi:[1,1,1]
	v_pk_fma_f32 v[12:13], v[124:125], v[34:35], v[12:13] op_sel:[0,1,0] op_sel_hi:[1,1,1]
	v_pk_fma_f32 v[14:15], v[126:127], v[34:35], v[14:15] op_sel:[0,1,0] op_sel_hi:[1,1,1]
	s_waitcnt vmcnt(21)
	v_cvt_pk_f32_fp8_e32 v[112:113], v64
	v_cvt_pk_f32_fp8_sdwa v[114:115], v64 src0_sel:WORD_1
	v_cvt_pk_f32_fp8_e32 v[116:117], v65
	v_cvt_pk_f32_fp8_sdwa v[118:119], v65 src0_sel:WORD_1
	v_cvt_pk_f32_fp8_e32 v[120:121], v66
	v_cvt_pk_f32_fp8_sdwa v[122:123], v66 src0_sel:WORD_1
	v_cvt_pk_f32_fp8_e32 v[124:125], v67
	v_cvt_pk_f32_fp8_sdwa v[126:127], v67 src0_sel:WORD_1
	global_load_dwordx4 v[64:67], v20, s[40:41]
	v_pk_fma_f32 v[0:1], v[112:113], v[36:37], v[0:1] op_sel_hi:[1,0,1]
	v_pk_fma_f32 v[2:3], v[114:115], v[36:37], v[2:3] op_sel_hi:[1,0,1]
	v_pk_fma_f32 v[4:5], v[116:117], v[36:37], v[4:5] op_sel_hi:[1,0,1]
	v_pk_fma_f32 v[6:7], v[118:119], v[36:37], v[6:7] op_sel_hi:[1,0,1]
	v_pk_fma_f32 v[8:9], v[120:121], v[36:37], v[8:9] op_sel_hi:[1,0,1]
	v_pk_fma_f32 v[10:11], v[122:123], v[36:37], v[10:11] op_sel_hi:[1,0,1]
	v_pk_fma_f32 v[12:13], v[124:125], v[36:37], v[12:13] op_sel_hi:[1,0,1]
	v_pk_fma_f32 v[14:15], v[126:127], v[36:37], v[14:15] op_sel_hi:[1,0,1]
	s_waitcnt vmcnt(21)
	v_cvt_pk_f32_fp8_e32 v[112:113], v68
	v_cvt_pk_f32_fp8_sdwa v[114:115], v68 src0_sel:WORD_1
	v_cvt_pk_f32_fp8_e32 v[116:117], v69
	v_cvt_pk_f32_fp8_sdwa v[118:119], v69 src0_sel:WORD_1
	v_cvt_pk_f32_fp8_e32 v[120:121], v70
	v_cvt_pk_f32_fp8_sdwa v[122:123], v70 src0_sel:WORD_1
	v_cvt_pk_f32_fp8_e32 v[124:125], v71
	v_cvt_pk_f32_fp8_sdwa v[126:127], v71 src0_sel:WORD_1
	global_load_dwordx4 v[68:71], v21, s[40:41]
	v_pk_fma_f32 v[0:1], v[112:113], v[36:37], v[0:1] op_sel:[0,1,0] op_sel_hi:[1,1,1]
	v_pk_fma_f32 v[2:3], v[114:115], v[36:37], v[2:3] op_sel:[0,1,0] op_sel_hi:[1,1,1]
	v_pk_fma_f32 v[4:5], v[116:117], v[36:37], v[4:5] op_sel:[0,1,0] op_sel_hi:[1,1,1]
	v_pk_fma_f32 v[6:7], v[118:119], v[36:37], v[6:7] op_sel:[0,1,0] op_sel_hi:[1,1,1]
	v_pk_fma_f32 v[8:9], v[120:121], v[36:37], v[8:9] op_sel:[0,1,0] op_sel_hi:[1,1,1]
	v_pk_fma_f32 v[10:11], v[122:123], v[36:37], v[10:11] op_sel:[0,1,0] op_sel_hi:[1,1,1]
	v_pk_fma_f32 v[12:13], v[124:125], v[36:37], v[12:13] op_sel:[0,1,0] op_sel_hi:[1,1,1]
	v_pk_fma_f32 v[14:15], v[126:127], v[36:37], v[14:15] op_sel:[0,1,0] op_sel_hi:[1,1,1]
	s_waitcnt vmcnt(21)
	v_cvt_pk_f32_fp8_e32 v[112:113], v72
	v_cvt_pk_f32_fp8_sdwa v[114:115], v72 src0_sel:WORD_1
	v_cvt_pk_f32_fp8_e32 v[116:117], v73
	v_cvt_pk_f32_fp8_sdwa v[118:119], v73 src0_sel:WORD_1
	v_cvt_pk_f32_fp8_e32 v[120:121], v74
	v_cvt_pk_f32_fp8_sdwa v[122:123], v74 src0_sel:WORD_1
	v_cvt_pk_f32_fp8_e32 v[124:125], v75
	v_cvt_pk_f32_fp8_sdwa v[126:127], v75 src0_sel:WORD_1
	global_load_dwordx4 v[72:75], v22, s[40:41]
	v_pk_fma_f32 v[0:1], v[112:113], v[38:39], v[0:1] op_sel_hi:[1,0,1]
	v_pk_fma_f32 v[2:3], v[114:115], v[38:39], v[2:3] op_sel_hi:[1,0,1]
	v_pk_fma_f32 v[4:5], v[116:117], v[38:39], v[4:5] op_sel_hi:[1,0,1]
	v_pk_fma_f32 v[6:7], v[118:119], v[38:39], v[6:7] op_sel_hi:[1,0,1]
	v_pk_fma_f32 v[8:9], v[120:121], v[38:39], v[8:9] op_sel_hi:[1,0,1]
	v_pk_fma_f32 v[10:11], v[122:123], v[38:39], v[10:11] op_sel_hi:[1,0,1]
	v_pk_fma_f32 v[12:13], v[124:125], v[38:39], v[12:13] op_sel_hi:[1,0,1]
	v_pk_fma_f32 v[14:15], v[126:127], v[38:39], v[14:15] op_sel_hi:[1,0,1]
	s_waitcnt vmcnt(21)
	v_cvt_pk_f32_fp8_e32 v[112:113], v76
	v_cvt_pk_f32_fp8_sdwa v[114:115], v76 src0_sel:WORD_1
	v_cvt_pk_f32_fp8_e32 v[116:117], v77
	v_cvt_pk_f32_fp8_sdwa v[118:119], v77 src0_sel:WORD_1
	v_cvt_pk_f32_fp8_e32 v[120:121], v78
	v_cvt_pk_f32_fp8_sdwa v[122:123], v78 src0_sel:WORD_1
	v_cvt_pk_f32_fp8_e32 v[124:125], v79
	v_cvt_pk_f32_fp8_sdwa v[126:127], v79 src0_sel:WORD_1
	global_load_dwordx4 v[76:79], v23, s[40:41]
	v_pk_fma_f32 v[0:1], v[112:113], v[38:39], v[0:1] op_sel:[0,1,0] op_sel_hi:[1,1,1]
	v_pk_fma_f32 v[2:3], v[114:115], v[38:39], v[2:3] op_sel:[0,1,0] op_sel_hi:[1,1,1]
	v_pk_fma_f32 v[4:5], v[116:117], v[38:39], v[4:5] op_sel:[0,1,0] op_sel_hi:[1,1,1]
	v_pk_fma_f32 v[6:7], v[118:119], v[38:39], v[6:7] op_sel:[0,1,0] op_sel_hi:[1,1,1]
	v_pk_fma_f32 v[8:9], v[120:121], v[38:39], v[8:9] op_sel:[0,1,0] op_sel_hi:[1,1,1]
	v_pk_fma_f32 v[10:11], v[122:123], v[38:39], v[10:11] op_sel:[0,1,0] op_sel_hi:[1,1,1]
	v_pk_fma_f32 v[12:13], v[124:125], v[38:39], v[12:13] op_sel:[0,1,0] op_sel_hi:[1,1,1]
	v_pk_fma_f32 v[14:15], v[126:127], v[38:39], v[14:15] op_sel:[0,1,0] op_sel_hi:[1,1,1]
	s_waitcnt vmcnt(21)
	v_cvt_pk_f32_fp8_e32 v[112:113], v80
	v_cvt_pk_f32_fp8_sdwa v[114:115], v80 src0_sel:WORD_1
	v_cvt_pk_f32_fp8_e32 v[116:117], v81
	v_cvt_pk_f32_fp8_sdwa v[118:119], v81 src0_sel:WORD_1
	v_cvt_pk_f32_fp8_e32 v[120:121], v82
	v_cvt_pk_f32_fp8_sdwa v[122:123], v82 src0_sel:WORD_1
	v_cvt_pk_f32_fp8_e32 v[124:125], v83
	v_cvt_pk_f32_fp8_sdwa v[126:127], v83 src0_sel:WORD_1
	global_load_dwordx4 v[80:83], v24, s[40:41]
	v_pk_fma_f32 v[0:1], v[112:113], v[40:41], v[0:1] op_sel_hi:[1,0,1]
	v_pk_fma_f32 v[2:3], v[114:115], v[40:41], v[2:3] op_sel_hi:[1,0,1]
	v_pk_fma_f32 v[4:5], v[116:117], v[40:41], v[4:5] op_sel_hi:[1,0,1]
	v_pk_fma_f32 v[6:7], v[118:119], v[40:41], v[6:7] op_sel_hi:[1,0,1]
	v_pk_fma_f32 v[8:9], v[120:121], v[40:41], v[8:9] op_sel_hi:[1,0,1]
	v_pk_fma_f32 v[10:11], v[122:123], v[40:41], v[10:11] op_sel_hi:[1,0,1]
	v_pk_fma_f32 v[12:13], v[124:125], v[40:41], v[12:13] op_sel_hi:[1,0,1]
	v_pk_fma_f32 v[14:15], v[126:127], v[40:41], v[14:15] op_sel_hi:[1,0,1]
	s_waitcnt vmcnt(21)
	v_cvt_pk_f32_fp8_e32 v[112:113], v84
	v_cvt_pk_f32_fp8_sdwa v[114:115], v84 src0_sel:WORD_1
	v_cvt_pk_f32_fp8_e32 v[116:117], v85
	v_cvt_pk_f32_fp8_sdwa v[118:119], v85 src0_sel:WORD_1
	v_cvt_pk_f32_fp8_e32 v[120:121], v86
	v_cvt_pk_f32_fp8_sdwa v[122:123], v86 src0_sel:WORD_1
	v_cvt_pk_f32_fp8_e32 v[124:125], v87
	v_cvt_pk_f32_fp8_sdwa v[126:127], v87 src0_sel:WORD_1
	global_load_dwordx4 v[84:87], v25, s[40:41]
	v_pk_fma_f32 v[0:1], v[112:113], v[40:41], v[0:1] op_sel:[0,1,0] op_sel_hi:[1,1,1]
	v_pk_fma_f32 v[2:3], v[114:115], v[40:41], v[2:3] op_sel:[0,1,0] op_sel_hi:[1,1,1]
	v_pk_fma_f32 v[4:5], v[116:117], v[40:41], v[4:5] op_sel:[0,1,0] op_sel_hi:[1,1,1]
	v_pk_fma_f32 v[6:7], v[118:119], v[40:41], v[6:7] op_sel:[0,1,0] op_sel_hi:[1,1,1]
	v_pk_fma_f32 v[8:9], v[120:121], v[40:41], v[8:9] op_sel:[0,1,0] op_sel_hi:[1,1,1]
	v_pk_fma_f32 v[10:11], v[122:123], v[40:41], v[10:11] op_sel:[0,1,0] op_sel_hi:[1,1,1]
	v_pk_fma_f32 v[12:13], v[124:125], v[40:41], v[12:13] op_sel:[0,1,0] op_sel_hi:[1,1,1]
	v_pk_fma_f32 v[14:15], v[126:127], v[40:41], v[14:15] op_sel:[0,1,0] op_sel_hi:[1,1,1]
	s_waitcnt vmcnt(21)
	v_cvt_pk_f32_fp8_e32 v[112:113], v88
	v_cvt_pk_f32_fp8_sdwa v[114:115], v88 src0_sel:WORD_1
	v_cvt_pk_f32_fp8_e32 v[116:117], v89
	v_cvt_pk_f32_fp8_sdwa v[118:119], v89 src0_sel:WORD_1
	v_cvt_pk_f32_fp8_e32 v[120:121], v90
	v_cvt_pk_f32_fp8_sdwa v[122:123], v90 src0_sel:WORD_1
	v_cvt_pk_f32_fp8_e32 v[124:125], v91
	v_cvt_pk_f32_fp8_sdwa v[126:127], v91 src0_sel:WORD_1
	global_load_dwordx4 v[88:91], v26, s[40:41]
	v_pk_fma_f32 v[0:1], v[112:113], v[42:43], v[0:1] op_sel_hi:[1,0,1]
	v_pk_fma_f32 v[2:3], v[114:115], v[42:43], v[2:3] op_sel_hi:[1,0,1]
	v_pk_fma_f32 v[4:5], v[116:117], v[42:43], v[4:5] op_sel_hi:[1,0,1]
	v_pk_fma_f32 v[6:7], v[118:119], v[42:43], v[6:7] op_sel_hi:[1,0,1]
	v_pk_fma_f32 v[8:9], v[120:121], v[42:43], v[8:9] op_sel_hi:[1,0,1]
	v_pk_fma_f32 v[10:11], v[122:123], v[42:43], v[10:11] op_sel_hi:[1,0,1]
	v_pk_fma_f32 v[12:13], v[124:125], v[42:43], v[12:13] op_sel_hi:[1,0,1]
	v_pk_fma_f32 v[14:15], v[126:127], v[42:43], v[14:15] op_sel_hi:[1,0,1]
	s_waitcnt vmcnt(21)
	v_cvt_pk_f32_fp8_e32 v[112:113], v92
	v_cvt_pk_f32_fp8_sdwa v[114:115], v92 src0_sel:WORD_1
	v_cvt_pk_f32_fp8_e32 v[116:117], v93
	v_cvt_pk_f32_fp8_sdwa v[118:119], v93 src0_sel:WORD_1
	v_cvt_pk_f32_fp8_e32 v[120:121], v94
	v_cvt_pk_f32_fp8_sdwa v[122:123], v94 src0_sel:WORD_1
	v_cvt_pk_f32_fp8_e32 v[124:125], v95
	v_cvt_pk_f32_fp8_sdwa v[126:127], v95 src0_sel:WORD_1
	global_load_dwordx4 v[92:95], v27, s[40:41]
	v_pk_fma_f32 v[0:1], v[112:113], v[42:43], v[0:1] op_sel:[0,1,0] op_sel_hi:[1,1,1]
	v_pk_fma_f32 v[2:3], v[114:115], v[42:43], v[2:3] op_sel:[0,1,0] op_sel_hi:[1,1,1]
	v_pk_fma_f32 v[4:5], v[116:117], v[42:43], v[4:5] op_sel:[0,1,0] op_sel_hi:[1,1,1]
	v_pk_fma_f32 v[6:7], v[118:119], v[42:43], v[6:7] op_sel:[0,1,0] op_sel_hi:[1,1,1]
	v_pk_fma_f32 v[8:9], v[120:121], v[42:43], v[8:9] op_sel:[0,1,0] op_sel_hi:[1,1,1]
	v_pk_fma_f32 v[10:11], v[122:123], v[42:43], v[10:11] op_sel:[0,1,0] op_sel_hi:[1,1,1]
	v_pk_fma_f32 v[12:13], v[124:125], v[42:43], v[12:13] op_sel:[0,1,0] op_sel_hi:[1,1,1]
	v_pk_fma_f32 v[14:15], v[126:127], v[42:43], v[14:15] op_sel:[0,1,0] op_sel_hi:[1,1,1]
	s_waitcnt vmcnt(21)
	v_cvt_pk_f32_fp8_e32 v[112:113], v96
	v_cvt_pk_f32_fp8_sdwa v[114:115], v96 src0_sel:WORD_1
	v_cvt_pk_f32_fp8_e32 v[116:117], v97
	v_cvt_pk_f32_fp8_sdwa v[118:119], v97 src0_sel:WORD_1
	v_cvt_pk_f32_fp8_e32 v[120:121], v98
	v_cvt_pk_f32_fp8_sdwa v[122:123], v98 src0_sel:WORD_1
	v_cvt_pk_f32_fp8_e32 v[124:125], v99
	v_cvt_pk_f32_fp8_sdwa v[126:127], v99 src0_sel:WORD_1
	global_load_dwordx4 v[96:99], v28, s[40:41]
	v_pk_fma_f32 v[0:1], v[112:113], v[44:45], v[0:1] op_sel_hi:[1,0,1]
	v_pk_fma_f32 v[2:3], v[114:115], v[44:45], v[2:3] op_sel_hi:[1,0,1]
	v_pk_fma_f32 v[4:5], v[116:117], v[44:45], v[4:5] op_sel_hi:[1,0,1]
	v_pk_fma_f32 v[6:7], v[118:119], v[44:45], v[6:7] op_sel_hi:[1,0,1]
	v_pk_fma_f32 v[8:9], v[120:121], v[44:45], v[8:9] op_sel_hi:[1,0,1]
	v_pk_fma_f32 v[10:11], v[122:123], v[44:45], v[10:11] op_sel_hi:[1,0,1]
	v_pk_fma_f32 v[12:13], v[124:125], v[44:45], v[12:13] op_sel_hi:[1,0,1]
	v_pk_fma_f32 v[14:15], v[126:127], v[44:45], v[14:15] op_sel_hi:[1,0,1]
	s_waitcnt vmcnt(21)
	v_cvt_pk_f32_fp8_e32 v[112:113], v100
	v_cvt_pk_f32_fp8_sdwa v[114:115], v100 src0_sel:WORD_1
	v_cvt_pk_f32_fp8_e32 v[116:117], v101
	v_cvt_pk_f32_fp8_sdwa v[118:119], v101 src0_sel:WORD_1
	v_cvt_pk_f32_fp8_e32 v[120:121], v102
	v_cvt_pk_f32_fp8_sdwa v[122:123], v102 src0_sel:WORD_1
	v_cvt_pk_f32_fp8_e32 v[124:125], v103
	v_cvt_pk_f32_fp8_sdwa v[126:127], v103 src0_sel:WORD_1
	global_load_dwordx4 v[100:103], v29, s[40:41]
	v_pk_fma_f32 v[0:1], v[112:113], v[44:45], v[0:1] op_sel:[0,1,0] op_sel_hi:[1,1,1]
	v_pk_fma_f32 v[2:3], v[114:115], v[44:45], v[2:3] op_sel:[0,1,0] op_sel_hi:[1,1,1]
	v_pk_fma_f32 v[4:5], v[116:117], v[44:45], v[4:5] op_sel:[0,1,0] op_sel_hi:[1,1,1]
	v_pk_fma_f32 v[6:7], v[118:119], v[44:45], v[6:7] op_sel:[0,1,0] op_sel_hi:[1,1,1]
	v_pk_fma_f32 v[8:9], v[120:121], v[44:45], v[8:9] op_sel:[0,1,0] op_sel_hi:[1,1,1]
	v_pk_fma_f32 v[10:11], v[122:123], v[44:45], v[10:11] op_sel:[0,1,0] op_sel_hi:[1,1,1]
	v_pk_fma_f32 v[12:13], v[124:125], v[44:45], v[12:13] op_sel:[0,1,0] op_sel_hi:[1,1,1]
	v_pk_fma_f32 v[14:15], v[126:127], v[44:45], v[14:15] op_sel:[0,1,0] op_sel_hi:[1,1,1]
	s_waitcnt vmcnt(21)
	v_cvt_pk_f32_fp8_e32 v[112:113], v104
	v_cvt_pk_f32_fp8_sdwa v[114:115], v104 src0_sel:WORD_1
	v_cvt_pk_f32_fp8_e32 v[116:117], v105
	v_cvt_pk_f32_fp8_sdwa v[118:119], v105 src0_sel:WORD_1
	v_cvt_pk_f32_fp8_e32 v[120:121], v106
	v_cvt_pk_f32_fp8_sdwa v[122:123], v106 src0_sel:WORD_1
	v_cvt_pk_f32_fp8_e32 v[124:125], v107
	v_cvt_pk_f32_fp8_sdwa v[126:127], v107 src0_sel:WORD_1
	global_load_dwordx4 v[104:107], v30, s[40:41]
	v_pk_fma_f32 v[0:1], v[112:113], v[46:47], v[0:1] op_sel_hi:[1,0,1]
	v_pk_fma_f32 v[2:3], v[114:115], v[46:47], v[2:3] op_sel_hi:[1,0,1]
	v_pk_fma_f32 v[4:5], v[116:117], v[46:47], v[4:5] op_sel_hi:[1,0,1]
	v_pk_fma_f32 v[6:7], v[118:119], v[46:47], v[6:7] op_sel_hi:[1,0,1]
	v_pk_fma_f32 v[8:9], v[120:121], v[46:47], v[8:9] op_sel_hi:[1,0,1]
	v_pk_fma_f32 v[10:11], v[122:123], v[46:47], v[10:11] op_sel_hi:[1,0,1]
	v_pk_fma_f32 v[12:13], v[124:125], v[46:47], v[12:13] op_sel_hi:[1,0,1]
	v_pk_fma_f32 v[14:15], v[126:127], v[46:47], v[14:15] op_sel_hi:[1,0,1]
	s_waitcnt vmcnt(21)
	v_cvt_pk_f32_fp8_e32 v[112:113], v108
	v_cvt_pk_f32_fp8_sdwa v[114:115], v108 src0_sel:WORD_1
	v_cvt_pk_f32_fp8_e32 v[116:117], v109
	v_cvt_pk_f32_fp8_sdwa v[118:119], v109 src0_sel:WORD_1
	v_cvt_pk_f32_fp8_e32 v[120:121], v110
	v_cvt_pk_f32_fp8_sdwa v[122:123], v110 src0_sel:WORD_1
	v_cvt_pk_f32_fp8_e32 v[124:125], v111
	v_cvt_pk_f32_fp8_sdwa v[126:127], v111 src0_sel:WORD_1
	global_load_dwordx4 v[108:111], v31, s[40:41]
	v_pk_fma_f32 v[0:1], v[112:113], v[46:47], v[0:1] op_sel:[0,1,0] op_sel_hi:[1,1,1]
	v_pk_fma_f32 v[2:3], v[114:115], v[46:47], v[2:3] op_sel:[0,1,0] op_sel_hi:[1,1,1]
	v_pk_fma_f32 v[4:5], v[116:117], v[46:47], v[4:5] op_sel:[0,1,0] op_sel_hi:[1,1,1]
	v_pk_fma_f32 v[6:7], v[118:119], v[46:47], v[6:7] op_sel:[0,1,0] op_sel_hi:[1,1,1]
	v_pk_fma_f32 v[8:9], v[120:121], v[46:47], v[8:9] op_sel:[0,1,0] op_sel_hi:[1,1,1]
	v_pk_fma_f32 v[10:11], v[122:123], v[46:47], v[10:11] op_sel:[0,1,0] op_sel_hi:[1,1,1]
	v_pk_fma_f32 v[12:13], v[124:125], v[46:47], v[12:13] op_sel:[0,1,0] op_sel_hi:[1,1,1]
	v_pk_fma_f32 v[14:15], v[126:127], v[46:47], v[14:15] op_sel:[0,1,0] op_sel_hi:[1,1,1]
	s_nop 1
	v_permlane32_swap_b32_e32 v0, v8
	v_permlane32_swap_b32_e32 v1, v9
	v_permlane32_swap_b32_e32 v2, v10
	v_permlane32_swap_b32_e32 v3, v11
	v_permlane32_swap_b32_e32 v4, v12
	v_permlane32_swap_b32_e32 v5, v13
	v_permlane32_swap_b32_e32 v6, v14
	v_permlane32_swap_b32_e32 v7, v15
	v_add_f32_e32 v0, v0, v8
	v_add_f32_e32 v1, v1, v9
	v_add_f32_e32 v2, v2, v10
	v_add_f32_e32 v3, v3, v11
	v_add_f32_e32 v4, v4, v12
	v_add_f32_e32 v5, v5, v13
	v_add_f32_e32 v6, v6, v14
	v_add_f32_e32 v7, v7, v15
	s_nop 1
	v_permlane16_swap_b32_e32 v0, v4
	v_permlane16_swap_b32_e32 v1, v5
	v_permlane16_swap_b32_e32 v2, v6
	v_permlane16_swap_b32_e32 v3, v7
	v_add_f32_e32 v0, v0, v4
	v_add_f32_e32 v1, v1, v5
	v_add_f32_e32 v2, v2, v6
	v_add_f32_e32 v3, v3, v7
	s_nop 1
	v_add_f32_dpp v142, v0, v0 row_ror:8 row_mask:0xf bank_mask:0x3
	v_add_f32_dpp v142, v2, v2 row_ror:8 row_mask:0xf bank_mask:0xc
	v_add_f32_dpp v143, v1, v1 row_ror:8 row_mask:0xf bank_mask:0x3
	v_add_f32_dpp v143, v3, v3 row_ror:8 row_mask:0xf bank_mask:0xc
	v_mov_b32_e32 v0, v142
	v_mov_b32_e32 v1, v143
	s_waitcnt vmcnt(16)
	v_mul_f32_e32 v192, v0, v192
	v_mul_f32_e32 v193, v1, v193
	v_fma_f32 v190, v190, s16, v192
	v_fma_f32 v191, v191, s16, v193
	s_lshl_b32 s98, s54, 12
	s_add_u32 s52, s92, s98
	s_addc_u32 s53, s93, 0
	global_store_dwordx2 v188, v[190:191], s[52:53]
	s_waitcnt vmcnt(16)
	ds_bpermute_b32 v16, v130, v150
	ds_bpermute_b32 v17, v131, v150
	ds_bpermute_b32 v18, v132, v150
	ds_bpermute_b32 v19, v133, v150
	ds_bpermute_b32 v20, v134, v150
	ds_bpermute_b32 v21, v135, v150
	ds_bpermute_b32 v22, v136, v150
	ds_bpermute_b32 v23, v137, v150
	ds_bpermute_b32 v24, v130, v151
	ds_bpermute_b32 v25, v131, v151
	ds_bpermute_b32 v26, v132, v151
	ds_bpermute_b32 v27, v133, v151
	ds_bpermute_b32 v28, v134, v151
	ds_bpermute_b32 v29, v135, v151
	ds_bpermute_b32 v30, v136, v151
	ds_bpermute_b32 v31, v137, v151
	s_waitcnt lgkmcnt(0)
	v_lshl_add_u32 v16, v16, 10, v138
	v_lshl_add_u32 v17, v17, 10, v138
	v_lshl_add_u32 v18, v18, 10, v138
	v_lshl_add_u32 v19, v19, 10, v138
	v_lshl_add_u32 v20, v20, 10, v138
	v_lshl_add_u32 v21, v21, 10, v138
	v_lshl_add_u32 v22, v22, 10, v138
	v_lshl_add_u32 v23, v23, 10, v138
	v_lshl_add_u32 v24, v24, 10, v138
	v_lshl_add_u32 v25, v25, 10, v138
	v_lshl_add_u32 v26, v26, 10, v138
	v_lshl_add_u32 v27, v27, 10, v138
	v_lshl_add_u32 v28, v28, 10, v138
	v_lshl_add_u32 v29, v29, 10, v138
	v_lshl_add_u32 v30, v30, 10, v138
	v_lshl_add_u32 v31, v31, 10, v138
	ds_bpermute_b32 v32, v130, v194
	ds_bpermute_b32 v33, v131, v194
	ds_bpermute_b32 v34, v132, v194
	ds_bpermute_b32 v35, v133, v194
	ds_bpermute_b32 v36, v134, v194
	ds_bpermute_b32 v37, v135, v194
	ds_bpermute_b32 v38, v136, v194
	ds_bpermute_b32 v39, v137, v194
	ds_bpermute_b32 v40, v130, v195
	ds_bpermute_b32 v41, v131, v195
	ds_bpermute_b32 v42, v132, v195
	ds_bpermute_b32 v43, v133, v195
	ds_bpermute_b32 v44, v134, v195
	ds_bpermute_b32 v45, v135, v195
	ds_bpermute_b32 v46, v136, v195
	ds_bpermute_b32 v47, v137, v195
	s_mov_b32 s54, s99
	s_cmp_lt_u32 s54, 0x4200
	s_cbranch_scc1 .Lgy_Ctok_11

.Lgy_D_4:
	v_lshrrev_b32_e32 v142, 6, v162
	v_readlane_b32 s2, v242, 0
	v_readlane_b32 s59, v241, 24
	v_readfirstlane_b32 s29, v142
	s_lshl_b32 s2, s2, 2
	s_add_u32 s54, s2, s29
	s_load_dwordx4 s[92:95], s[0:1], 0xc0
	s_load_dwordx2 s[88:89], s[0:1], 0x120
	v_lshlrev_b32_e32 v160, 6, v168
	v_lshlrev_b32_e32 v161, 5, v168
	v_readlane_b32 s8, v240, 12
	v_readlane_b32 s9, v240, 13
	v_readlane_b32 s10, v240, 14
	v_readlane_b32 s11, v240, 15
	v_readlane_b32 s12, v240, 3
	v_readlane_b32 s13, v240, 5
	s_waitcnt lgkmcnt(0)
	s_nop 4
	global_load_dwordx4 v[80:83], v160, s[8:9] offset:0
	global_load_dwordx4 v[84:87], v160, s[8:9] offset:16
	global_load_dwordx4 v[88:91], v160, s[8:9] offset:32
	global_load_dwordx4 v[92:95], v160, s[8:9] offset:48
	global_load_dwordx4 v[96:99], v160, s[10:11] offset:0
	global_load_dwordx4 v[100:103], v160, s[10:11] offset:16
	global_load_dwordx4 v[104:107], v160, s[10:11] offset:32
	global_load_dwordx4 v[108:111], v160, s[10:11] offset:48
	s_cmp_lt_u32 s54, 0x4200
	s_cbranch_scc0 .Lgy_Ddone_13
.Lgy_Dtok_12:
	s_mov_b32 s2, s54
	s_lshl_b32 s50, s2, 12
	s_add_u32 s52, s88, s50
	s_addc_u32 s53, s89, 0
	global_load_dwordx4 v[48:51], v160, s[52:53] offset:0
	global_load_dwordx4 v[52:55], v160, s[52:53] offset:16
	global_load_dwordx4 v[56:59], v160, s[52:53] offset:32
	global_load_dwordx4 v[60:63], v160, s[52:53] offset:48
	s_cmp_lt_u32 s2, 0x2000
	s_cselect_b32 s14, 0, 1
	s_cmp_lt_u32 s2, 0x4000
	s_cselect_b32 s14, s14, 2
	s_cmp_lg_u32 s12, 0
	s_cbranch_scc0 .Lgy_nomod_14
	s_add_u32 s16, s14, s13
	s_mul_i32 s16, s16, 0x6000
	s_add_u32 s46, s94, s16
	s_addc_u32 s47, s95, 0
	global_load_dwordx4 v[112:115], v160, s[46:47] offset:0
	global_load_dwordx4 v[116:119], v160, s[46:47] offset:16
	global_load_dwordx4 v[120:123], v160, s[46:47] offset:32
	global_load_dwordx4 v[124:127], v160, s[46:47] offset:48
	s_add_u32 s46, s46, 0x1000
	s_addc_u32 s47, s47, 0
	global_load_dwordx4 v[130:133], v160, s[46:47] offset:0
	global_load_dwordx4 v[134:137], v160, s[46:47] offset:16
	global_load_dwordx4 v[138:141], v160, s[46:47] offset:32
	global_load_dwordx4 v[142:145], v160, s[46:47] offset:48
.Lgy_nomod_14:
	s_waitcnt vmcnt(0)
	v_add_f32_e32 v146, v48, v49
	v_add_f32_e32 v146, v146, v50
	v_add_f32_e32 v146, v146, v51
	v_add_f32_e32 v146, v146, v52
	v_add_f32_e32 v146, v146, v53
	v_add_f32_e32 v146, v146, v54
	v_add_f32_e32 v146, v146, v55
	v_add_f32_e32 v146, v146, v56
	v_add_f32_e32 v146, v146, v57
	v_add_f32_e32 v146, v146, v58
	v_add_f32_e32 v146, v146, v59
	v_add_f32_e32 v146, v146, v60
	v_add_f32_e32 v146, v146, v61
	v_add_f32_e32 v146, v146, v62
	v_add_f32_e32 v146, v146, v63
	s_nop 1
	v_add_f32_dpp v146, v146, v146 quad_perm:[1,0,3,2] row_mask:0xf bank_mask:0xf
	s_nop 1
	v_add_f32_dpp v146, v146, v146 quad_perm:[2,3,0,1] row_mask:0xf bank_mask:0xf
	s_nop 1
	v_add_f32_dpp v146, v146, v146 row_half_mirror row_mask:0xf bank_mask:0xf
	s_nop 1
	v_add_f32_dpp v146, v146, v146 row_mirror row_mask:0xf bank_mask:0xf
	s_nop 1
	v_readlane_b32 s4, v146, 0
	v_readlane_b32 s5, v146, 16
	v_readlane_b32 s6, v146, 32
	v_readlane_b32 s7, v146, 48
	s_nop 1
	v_mov_b32_e32 v147, s4
	v_add_f32_e32 v147, s5, v147
	v_add_f32_e32 v147, s6, v147
	v_add_f32_e32 v147, s7, v147
	v_mul_f32_e32 v147, 0x3a800000, v147
	v_sub_f32_e32 v48, v48, v147
	v_sub_f32_e32 v49, v49, v147
	v_sub_f32_e32 v50, v50, v147
	v_sub_f32_e32 v51, v51, v147
	v_sub_f32_e32 v52, v52, v147
	v_sub_f32_e32 v53, v53, v147
	v_sub_f32_e32 v54, v54, v147
	v_sub_f32_e32 v55, v55, v147
	v_sub_f32_e32 v56, v56, v147
	v_sub_f32_e32 v57, v57, v147
	v_sub_f32_e32 v58, v58, v147
	v_sub_f32_e32 v59, v59, v147
	v_sub_f32_e32 v60, v60, v147
	v_sub_f32_e32 v61, v61, v147
	v_sub_f32_e32 v62, v62, v147
	v_sub_f32_e32 v63, v63, v147
	v_mul_f32_e32 v146, v48, v48
	v_mul_f32_e32 v148, v49, v49
	v_add_f32_e32 v146, v146, v148
	v_mul_f32_e32 v148, v50, v50
	v_add_f32_e32 v146, v146, v148
	v_mul_f32_e32 v148, v51, v51
	v_add_f32_e32 v146, v146, v148
	v_mul_f32_e32 v148, v52, v52
	v_add_f32_e32 v146, v146, v148
	v_mul_f32_e32 v148, v53, v53
	v_add_f32_e32 v146, v146, v148
	v_mul_f32_e32 v148, v54, v54
	v_add_f32_e32 v146, v146, v148
	v_mul_f32_e32 v148, v55, v55
	v_add_f32_e32 v146, v146, v148
	v_mul_f32_e32 v148, v56, v56
	v_add_f32_e32 v146, v146, v148
	v_mul_f32_e32 v148, v57, v57
	v_add_f32_e32 v146, v146, v148
	v_mul_f32_e32 v148, v58, v58
	v_add_f32_e32 v146, v146, v148
	v_mul_f32_e32 v148, v59, v59
	v_add_f32_e32 v146, v146, v148
	v_mul_f32_e32 v148, v60, v60
	v_add_f32_e32 v146, v146, v148
	v_mul_f32_e32 v148, v61, v61
	v_add_f32_e32 v146, v146, v148
	v_mul_f32_e32 v148, v62, v62
	v_add_f32_e32 v146, v146, v148
	v_mul_f32_e32 v148, v63, v63
	v_add_f32_e32 v146, v146, v148
	s_nop 1
	v_add_f32_dpp v146, v146, v146 quad_perm:[1,0,3,2] row_mask:0xf bank_mask:0xf
	s_nop 1
	v_add_f32_dpp v146, v146, v146 quad_perm:[2,3,0,1] row_mask:0xf bank_mask:0xf
	s_nop 1
	v_add_f32_dpp v146, v146, v146 row_half_mirror row_mask:0xf bank_mask:0xf
	s_nop 1
	v_add_f32_dpp v146, v146, v146 row_mirror row_mask:0xf bank_mask:0xf
	s_nop 1
	v_readlane_b32 s4, v146, 0
	v_readlane_b32 s5, v146, 16
	v_readlane_b32 s6, v146, 32
	v_readlane_b32 s7, v146, 48
	s_nop 1
	v_mov_b32_e32 v147, s4
	v_add_f32_e32 v147, s5, v147
	v_add_f32_e32 v147, s6, v147
	v_add_f32_e32 v147, s7, v147
	v_fmamk_f32 v147, v147, 0x3a800000, v163
	s_mov_b32 s4, 0x800000
	v_cmp_gt_f32_e32 vcc, s4, v147
	v_mul_f32_e32 v148, 0x4b800000, v147
	s_nop 1
	v_cndmask_b32_e32 v147, v147, v148, vcc
	v_rsq_f32_e32 v147, v147
	s_nop 0
	v_mul_f32_e32 v148, 0x45800000, v147
	v_cndmask_b32_e32 v147, v147, v148, vcc
	v_mul_f32_e32 v48, v48, v147
	v_mul_f32_e32 v49, v49, v147
	v_mul_f32_e32 v50, v50, v147
	v_mul_f32_e32 v51, v51, v147
	v_mul_f32_e32 v52, v52, v147
	v_mul_f32_e32 v53, v53, v147
	v_mul_f32_e32 v54, v54, v147
	v_mul_f32_e32 v55, v55, v147
	v_mul_f32_e32 v56, v56, v147
	v_mul_f32_e32 v57, v57, v147
	v_mul_f32_e32 v58, v58, v147
	v_mul_f32_e32 v59, v59, v147
	v_mul_f32_e32 v60, v60, v147
	v_mul_f32_e32 v61, v61, v147
	v_mul_f32_e32 v62, v62, v147
	v_mul_f32_e32 v63, v63, v147
	v_fma_f32 v48, v80, v48, v96
	v_fma_f32 v49, v81, v49, v97
	v_fma_f32 v50, v82, v50, v98
	v_fma_f32 v51, v83, v51, v99
	v_fma_f32 v52, v84, v52, v100
	v_fma_f32 v53, v85, v53, v101
	v_fma_f32 v54, v86, v54, v102
	v_fma_f32 v55, v87, v55, v103
	v_fma_f32 v56, v88, v56, v104
	v_fma_f32 v57, v89, v57, v105
	v_fma_f32 v58, v90, v58, v106
	v_fma_f32 v59, v91, v59, v107
	v_fma_f32 v60, v92, v60, v108
	v_fma_f32 v61, v93, v61, v109
	v_fma_f32 v62, v94, v62, v110
	v_fma_f32 v63, v95, v63, v111
	s_cmp_lg_u32 s12, 0
	s_cbranch_scc0 .Lgy_lastlayer_15
	s_add_u32 s52, s70, s50
	s_addc_u32 s53, s71, 0
	global_store_dwordx4 v160, v[48:51], s[52:53] offset:0
	global_store_dwordx4 v160, v[52:55], s[52:53] offset:16
	global_store_dwordx4 v160, v[56:59], s[52:53] offset:32
	global_store_dwordx4 v160, v[60:63], s[52:53] offset:48
	v_add_f32_e32 v130, 1.0, v130
	v_add_f32_e32 v131, 1.0, v131
	v_add_f32_e32 v132, 1.0, v132
	v_add_f32_e32 v133, 1.0, v133
	v_add_f32_e32 v134, 1.0, v134
	v_add_f32_e32 v135, 1.0, v135
	v_add_f32_e32 v136, 1.0, v136
	v_add_f32_e32 v137, 1.0, v137
	v_add_f32_e32 v138, 1.0, v138
	v_add_f32_e32 v139, 1.0, v139
	v_add_f32_e32 v140, 1.0, v140
	v_add_f32_e32 v141, 1.0, v141
	v_add_f32_e32 v142, 1.0, v142
	v_add_f32_e32 v143, 1.0, v143
	v_add_f32_e32 v144, 1.0, v144
	v_add_f32_e32 v145, 1.0, v145
	v_fma_f32 v112, v48, v130, v112
	v_fma_f32 v113, v49, v131, v113
	v_fma_f32 v114, v50, v132, v114
	v_fma_f32 v115, v51, v133, v115
	v_fma_f32 v116, v52, v134, v116
	v_fma_f32 v117, v53, v135, v117
	v_fma_f32 v118, v54, v136, v118
	v_fma_f32 v119, v55, v137, v119
	v_fma_f32 v120, v56, v138, v120
	v_fma_f32 v121, v57, v139, v121
	v_fma_f32 v122, v58, v140, v122
	v_fma_f32 v123, v59, v141, v123
	v_fma_f32 v124, v60, v142, v124
	v_fma_f32 v125, v61, v143, v125
	v_fma_f32 v126, v62, v144, v126
	v_fma_f32 v127, v63, v145, v127
	v_cvt_pk_bf16_f32 v64, v112, v113
	v_cvt_pk_bf16_f32 v65, v114, v115
	v_cvt_pk_bf16_f32 v66, v116, v117
	v_cvt_pk_bf16_f32 v67, v118, v119
	v_cvt_pk_bf16_f32 v68, v120, v121
	v_cvt_pk_bf16_f32 v69, v122, v123
	v_cvt_pk_bf16_f32 v70, v124, v125
	v_cvt_pk_bf16_f32 v71, v126, v127
	s_lshl_b32 s50, s2, 11
	s_add_u32 s46, s74, s50
	s_addc_u32 s47, s75, 0
	global_store_dwordx4 v161, v[64:67], s[46:47]
	global_store_dwordx4 v161, v[68:71], s[46:47] offset:16
	s_branch .Lgy_stdone_16
.Lgy_lastlayer_15:
	s_cmp_lt_u32 s2, 0x4000
	s_cbranch_scc0 .Lgy_stdone_16
	s_add_u32 s46, s92, s50
	s_addc_u32 s47, s93, 0
	global_store_dwordx4 v160, v[48:51], s[46:47] offset:0
	global_store_dwordx4 v160, v[52:55], s[46:47] offset:16
	global_store_dwordx4 v160, v[56:59], s[46:47] offset:32
	global_store_dwordx4 v160, v[60:63], s[46:47] offset:48
.Lgy_stdone_16:
	s_nop 1
	s_add_u32 s54, s54, s59
	s_cmp_lt_u32 s54, 0x4200
	s_cbranch_scc1 .Lgy_Dtok_12
.Lgy_Ddone_13:
.Lgy_exit_5:
	s_waitcnt vmcnt(0) lgkmcnt(0)
	s_mov_b64 exec, -1
	s_mov_b64 s[30:31], -1
	s_branch .LBB1_48

.LBB1_1482:
	s_cmp_eq_u32 s26, 15
	v_readlane_b32 s6, v240, 1
	s_cselect_b64 s[4:5], -1, 0
	v_readlane_b32 s7, v240, 2
	s_and_b64 s[4:5], s[6:7], s[4:5]
	s_and_b64 vcc, exec, s[4:5]
	s_cbranch_vccz .LBB1_1483
	s_getpc_b64 s[98:99]
